# phase2 pool-window: first 8 prompt jobs per wave in a double-buffered loop (16 unmasked clamped-row loads per job, next job's loads in flight, 1/cnt hoisted)
# baseline (speedup 1.0000x reference)
.LBB0_253:
	s_cmp_lt_i32 s92, 3
	s_cselect_b64 s[0:1], -1, 0
	s_cmp_gt_i32 s93, 2
	s_cselect_b64 s[4:5], -1, 0
	s_and_b64 s[0:1], s[0:1], s[4:5]
	s_andn2_b64 vcc, exec, s[0:1]
	s_cbranch_vccnz .LBB0_489
	s_cmpk_gt_i32 s2, 0x107f
	s_cbranch_scc1 .LBB0_271
	v_lshlrev_b32_e32 v2, 3, v218
	v_bfe_u32 v1, v218, 4, 2
	v_and_b32_e32 v2, 0x78, v2
	v_lshl_or_b32 v2, v1, 7, v2
	v_and_b32_e32 v0, 63, v218
	v_lshlrev_b32_e32 v8, 1, v2
	v_mov_b32_e32 v9, 0
	v_lshl_add_u64 v[10:11], s[90:91], 0, v[8:9]
	v_lshlrev_b32_e32 v8, 4, v0
	v_lshl_add_u64 v[12:13], s[88:89], 0, v[8:9]
	v_lshlrev_b32_e32 v8, 2, v2
	v_lshlrev_b32_e64 v38, v1, 2
	v_lshl_add_u64 v[0:1], s[72:73], 0, v[8:9]
	s_mov_b64 s[0:1], 0x7010
	v_lshl_add_u64 v[14:15], v[0:1], 0, s[0:1]
	s_movk_i32 s0, 0xfc00
	s_mov_b32 s1, -1
	v_lshl_add_u64 v[16:17], v[10:11], 0, s[0:1]
	s_movk_i32 s3, 0x1200
	s_mov_b32 s8, s2
	s_cmpk_lg_i32 s94, 0x200
	s_cbranch_scc1 .Lpool_skip
	v_and_b32_e32 v172, 63, v218
	v_lshrrev_b32_e32 v173, 4, v172
	v_and_b32_e32 v174, 15, v172
	v_lshlrev_b32_e32 v175, 4, v172
	v_lshlrev_b32_e32 v174, 3, v174
	v_lshl_add_u32 v172, v173, 7, v174
	v_lshlrev_b32_e32 v172, 1, v172
	v_add_u32_e32 v172, 0xe00, v172
	v_lshlrev_b32_e64 v173, v173, 2
	v_lshrrev_b32_e32 v174, 6, v218
	s_lshl_b32 s21, s2, 2
	s_nop 1
	v_readfirstlane_b32 s20, v174
	s_nop 1
	s_add_i32 s20, s20, s21
	s_mov_b32 s22, s20
	s_add_i32 s21, s20, 1
	v_min_u32_e32 v173, s21, v173
	v_cvt_f32_u32_e32 v0, v173
	v_div_scale_f32 v1, s[0:1], v0, v0, 1.0
	v_rcp_f32_e32 v2, v1
	v_div_scale_f32 v3, vcc, 1.0, v0, 1.0
	v_fma_f32 v4, -v1, v2, 1.0
	v_fmac_f32_e32 v2, v4, v2
	v_mul_f32_e32 v4, v3, v2
	v_fma_f32 v5, -v1, v4, v3
	v_fmac_f32_e32 v4, v5, v2
	v_fma_f32 v1, -v1, v4, v3
	v_div_fmas_f32 v1, v1, v2, v4
	v_div_fixup_f32 v174, v1, v0, 1.0
	s_mov_b32 s21, s20
	s_max_i32 s21, s21, 0
	s_mul_i32 s21, s21, 0x1200
	s_add_u32 s24, s90, s21
	s_addc_u32 s25, s91, 0
	global_load_dwordx4 v[44:47], v172, s[24:25]
	s_sub_i32 s21, s20, 1
	s_max_i32 s21, s21, 0
	s_mul_i32 s21, s21, 0x1200
	s_add_u32 s24, s90, s21
	s_addc_u32 s25, s91, 0
	global_load_dwordx4 v[48:51], v172, s[24:25]
	s_sub_i32 s21, s20, 2
	s_max_i32 s21, s21, 0
	s_mul_i32 s21, s21, 0x1200
	s_add_u32 s24, s90, s21
	s_addc_u32 s25, s91, 0
	global_load_dwordx4 v[52:55], v172, s[24:25]
	s_sub_i32 s21, s20, 3
	s_max_i32 s21, s21, 0
	s_mul_i32 s21, s21, 0x1200
	s_add_u32 s24, s90, s21
	s_addc_u32 s25, s91, 0
	global_load_dwordx4 v[56:59], v172, s[24:25]
	s_sub_i32 s21, s20, 4
	s_max_i32 s21, s21, 0
	s_mul_i32 s21, s21, 0x1200
	s_add_u32 s24, s90, s21
	s_addc_u32 s25, s91, 0
	global_load_dwordx4 v[60:63], v172, s[24:25]
	s_sub_i32 s21, s20, 5
	s_max_i32 s21, s21, 0
	s_mul_i32 s21, s21, 0x1200
	s_add_u32 s24, s90, s21
	s_addc_u32 s25, s91, 0
	global_load_dwordx4 v[64:67], v172, s[24:25]
	s_sub_i32 s21, s20, 6
	s_max_i32 s21, s21, 0
	s_mul_i32 s21, s21, 0x1200
	s_add_u32 s24, s90, s21
	s_addc_u32 s25, s91, 0
	global_load_dwordx4 v[68:71], v172, s[24:25]
	s_sub_i32 s21, s20, 7
	s_max_i32 s21, s21, 0
	s_mul_i32 s21, s21, 0x1200
	s_add_u32 s24, s90, s21
	s_addc_u32 s25, s91, 0
	global_load_dwordx4 v[72:75], v172, s[24:25]
	s_sub_i32 s21, s20, 8
	s_max_i32 s21, s21, 0
	s_mul_i32 s21, s21, 0x1200
	s_add_u32 s24, s90, s21
	s_addc_u32 s25, s91, 0
	global_load_dwordx4 v[76:79], v172, s[24:25]
	s_sub_i32 s21, s20, 9
	s_max_i32 s21, s21, 0
	s_mul_i32 s21, s21, 0x1200
	s_add_u32 s24, s90, s21
	s_addc_u32 s25, s91, 0
	global_load_dwordx4 v[80:83], v172, s[24:25]
	s_sub_i32 s21, s20, 10
	s_max_i32 s21, s21, 0
	s_mul_i32 s21, s21, 0x1200
	s_add_u32 s24, s90, s21
	s_addc_u32 s25, s91, 0
	global_load_dwordx4 v[84:87], v172, s[24:25]
	s_sub_i32 s21, s20, 11
	s_max_i32 s21, s21, 0
	s_mul_i32 s21, s21, 0x1200
	s_add_u32 s24, s90, s21
	s_addc_u32 s25, s91, 0
	global_load_dwordx4 v[88:91], v172, s[24:25]
	s_sub_i32 s21, s20, 12
	s_max_i32 s21, s21, 0
	s_mul_i32 s21, s21, 0x1200
	s_add_u32 s24, s90, s21
	s_addc_u32 s25, s91, 0
	global_load_dwordx4 v[92:95], v172, s[24:25]
	s_sub_i32 s21, s20, 13
	s_max_i32 s21, s21, 0
	s_mul_i32 s21, s21, 0x1200
	s_add_u32 s24, s90, s21
	s_addc_u32 s25, s91, 0
	global_load_dwordx4 v[96:99], v172, s[24:25]
	s_sub_i32 s21, s20, 14
	s_max_i32 s21, s21, 0
	s_mul_i32 s21, s21, 0x1200
	s_add_u32 s24, s90, s21
	s_addc_u32 s25, s91, 0
	global_load_dwordx4 v[100:103], v172, s[24:25]
	s_sub_i32 s21, s20, 15
	s_max_i32 s21, s21, 0
	s_mul_i32 s21, s21, 0x1200
	s_add_u32 s24, s90, s21
	s_addc_u32 s25, s91, 0
	global_load_dwordx4 v[104:107], v172, s[24:25]
	s_add_i32 s20, s20, 0x800
	s_mov_b32 s21, s20
	s_max_i32 s21, s21, 0
	s_mul_i32 s21, s21, 0x1200
	s_add_u32 s24, s90, s21
	s_addc_u32 s25, s91, 0
	global_load_dwordx4 v[108:111], v172, s[24:25]
	s_sub_i32 s21, s20, 1
	s_max_i32 s21, s21, 0
	s_mul_i32 s21, s21, 0x1200
	s_add_u32 s24, s90, s21
	s_addc_u32 s25, s91, 0
	global_load_dwordx4 v[112:115], v172, s[24:25]
	s_sub_i32 s21, s20, 2
	s_max_i32 s21, s21, 0
	s_mul_i32 s21, s21, 0x1200
	s_add_u32 s24, s90, s21
	s_addc_u32 s25, s91, 0
	global_load_dwordx4 v[116:119], v172, s[24:25]
	s_sub_i32 s21, s20, 3
	s_max_i32 s21, s21, 0
	s_mul_i32 s21, s21, 0x1200
	s_add_u32 s24, s90, s21
	s_addc_u32 s25, s91, 0
	global_load_dwordx4 v[120:123], v172, s[24:25]
	s_sub_i32 s21, s20, 4
	s_max_i32 s21, s21, 0
	s_mul_i32 s21, s21, 0x1200
	s_add_u32 s24, s90, s21
	s_addc_u32 s25, s91, 0
	global_load_dwordx4 v[124:127], v172, s[24:25]
	s_sub_i32 s21, s20, 5
	s_max_i32 s21, s21, 0
	s_mul_i32 s21, s21, 0x1200
	s_add_u32 s24, s90, s21
	s_addc_u32 s25, s91, 0
	global_load_dwordx4 v[128:131], v172, s[24:25]
	s_sub_i32 s21, s20, 6
	s_max_i32 s21, s21, 0
	s_mul_i32 s21, s21, 0x1200
	s_add_u32 s24, s90, s21
	s_addc_u32 s25, s91, 0
	global_load_dwordx4 v[132:135], v172, s[24:25]
	s_sub_i32 s21, s20, 7
	s_max_i32 s21, s21, 0
	s_mul_i32 s21, s21, 0x1200
	s_add_u32 s24, s90, s21
	s_addc_u32 s25, s91, 0
	global_load_dwordx4 v[136:139], v172, s[24:25]
	s_sub_i32 s21, s20, 8
	s_max_i32 s21, s21, 0
	s_mul_i32 s21, s21, 0x1200
	s_add_u32 s24, s90, s21
	s_addc_u32 s25, s91, 0
	global_load_dwordx4 v[140:143], v172, s[24:25]
	s_sub_i32 s21, s20, 9
	s_max_i32 s21, s21, 0
	s_mul_i32 s21, s21, 0x1200
	s_add_u32 s24, s90, s21
	s_addc_u32 s25, s91, 0
	global_load_dwordx4 v[144:147], v172, s[24:25]
	s_sub_i32 s21, s20, 10
	s_max_i32 s21, s21, 0
	s_mul_i32 s21, s21, 0x1200
	s_add_u32 s24, s90, s21
	s_addc_u32 s25, s91, 0
	global_load_dwordx4 v[148:151], v172, s[24:25]
	s_sub_i32 s21, s20, 11
	s_max_i32 s21, s21, 0
	s_mul_i32 s21, s21, 0x1200
	s_add_u32 s24, s90, s21
	s_addc_u32 s25, s91, 0
	global_load_dwordx4 v[152:155], v172, s[24:25]
	s_sub_i32 s21, s20, 12
	s_max_i32 s21, s21, 0
	s_mul_i32 s21, s21, 0x1200
	s_add_u32 s24, s90, s21
	s_addc_u32 s25, s91, 0
	global_load_dwordx4 v[156:159], v172, s[24:25]
	s_sub_i32 s21, s20, 13
	s_max_i32 s21, s21, 0
	s_mul_i32 s21, s21, 0x1200
	s_add_u32 s24, s90, s21
	s_addc_u32 s25, s91, 0
	global_load_dwordx4 v[160:163], v172, s[24:25]
	s_sub_i32 s21, s20, 14
	s_max_i32 s21, s21, 0
	s_mul_i32 s21, s21, 0x1200
	s_add_u32 s24, s90, s21
	s_addc_u32 s25, s91, 0
	global_load_dwordx4 v[164:167], v172, s[24:25]
	s_sub_i32 s21, s20, 15
	s_max_i32 s21, s21, 0
	s_mul_i32 s21, s21, 0x1200
	s_add_u32 s24, s90, s21
	s_addc_u32 s25, s91, 0
	global_load_dwordx4 v[168:171], v172, s[24:25]
	s_waitcnt vmcnt(16)
	v_lshlrev_b32_e32 v182, 16, v44
	v_and_b32_e32 v183, 0xffff0000, v44
	v_lshlrev_b32_e32 v180, 16, v45
	v_and_b32_e32 v181, 0xffff0000, v45
	v_lshlrev_b32_e32 v178, 16, v46
	v_and_b32_e32 v179, 0xffff0000, v46
	v_lshlrev_b32_e32 v176, 16, v47
	v_and_b32_e32 v177, 0xffff0000, v47
	v_mov_b32_e32 v184, v176
	v_mov_b32_e32 v185, v177
	v_mov_b32_e32 v186, v178
	v_mov_b32_e32 v187, v179
	v_mov_b32_e32 v188, v180
	v_mov_b32_e32 v189, v181
	v_mov_b32_e32 v190, v182
	v_mov_b32_e32 v191, v183
	s_mov_b64 s[26:27], exec
	v_cmp_lt_u32_e32 vcc, 1, v173
	s_and_b64 exec, exec, vcc
	v_lshlrev_b32_e32 v198, 16, v48
	v_and_b32_e32 v199, 0xffff0000, v48
	v_lshlrev_b32_e32 v196, 16, v49
	v_and_b32_e32 v197, 0xffff0000, v49
	v_lshlrev_b32_e32 v194, 16, v50
	v_and_b32_e32 v195, 0xffff0000, v50
	v_lshlrev_b32_e32 v192, 16, v51
	v_and_b32_e32 v193, 0xffff0000, v51
	v_pk_add_f32 v[184:185], v[184:185], v[192:193]
	v_pk_add_f32 v[186:187], v[186:187], v[194:195]
	v_pk_add_f32 v[188:189], v[188:189], v[196:197]
	v_pk_add_f32 v[190:191], v[190:191], v[198:199]
	v_cmp_lt_u32_e32 vcc, 2, v173
	s_and_b64 exec, exec, vcc
	v_lshlrev_b32_e32 v198, 16, v52
	v_and_b32_e32 v199, 0xffff0000, v52
	v_lshlrev_b32_e32 v196, 16, v53
	v_and_b32_e32 v197, 0xffff0000, v53
	v_lshlrev_b32_e32 v194, 16, v54
	v_and_b32_e32 v195, 0xffff0000, v54
	v_lshlrev_b32_e32 v192, 16, v55
	v_and_b32_e32 v193, 0xffff0000, v55
	v_pk_add_f32 v[184:185], v[184:185], v[192:193]
	v_pk_add_f32 v[186:187], v[186:187], v[194:195]
	v_pk_add_f32 v[188:189], v[188:189], v[196:197]
	v_pk_add_f32 v[190:191], v[190:191], v[198:199]
	v_cmp_lt_u32_e32 vcc, 3, v173
	s_and_b64 exec, exec, vcc
	v_lshlrev_b32_e32 v198, 16, v56
	v_and_b32_e32 v199, 0xffff0000, v56
	v_lshlrev_b32_e32 v196, 16, v57
	v_and_b32_e32 v197, 0xffff0000, v57
	v_lshlrev_b32_e32 v194, 16, v58
	v_and_b32_e32 v195, 0xffff0000, v58
	v_lshlrev_b32_e32 v192, 16, v59
	v_and_b32_e32 v193, 0xffff0000, v59
	v_pk_add_f32 v[184:185], v[184:185], v[192:193]
	v_pk_add_f32 v[186:187], v[186:187], v[194:195]
	v_pk_add_f32 v[188:189], v[188:189], v[196:197]
	v_pk_add_f32 v[190:191], v[190:191], v[198:199]
	v_cmp_lt_u32_e32 vcc, 4, v173
	s_and_b64 exec, exec, vcc
	v_lshlrev_b32_e32 v198, 16, v60
	v_and_b32_e32 v199, 0xffff0000, v60
	v_lshlrev_b32_e32 v196, 16, v61
	v_and_b32_e32 v197, 0xffff0000, v61
	v_lshlrev_b32_e32 v194, 16, v62
	v_and_b32_e32 v195, 0xffff0000, v62
	v_lshlrev_b32_e32 v192, 16, v63
	v_and_b32_e32 v193, 0xffff0000, v63
	v_pk_add_f32 v[184:185], v[184:185], v[192:193]
	v_pk_add_f32 v[186:187], v[186:187], v[194:195]
	v_pk_add_f32 v[188:189], v[188:189], v[196:197]
	v_pk_add_f32 v[190:191], v[190:191], v[198:199]
	v_cmp_lt_u32_e32 vcc, 5, v173
	s_and_b64 exec, exec, vcc
	v_lshlrev_b32_e32 v198, 16, v64
	v_and_b32_e32 v199, 0xffff0000, v64
	v_lshlrev_b32_e32 v196, 16, v65
	v_and_b32_e32 v197, 0xffff0000, v65
	v_lshlrev_b32_e32 v194, 16, v66
	v_and_b32_e32 v195, 0xffff0000, v66
	v_lshlrev_b32_e32 v192, 16, v67
	v_and_b32_e32 v193, 0xffff0000, v67
	v_pk_add_f32 v[184:185], v[184:185], v[192:193]
	v_pk_add_f32 v[186:187], v[186:187], v[194:195]
	v_pk_add_f32 v[188:189], v[188:189], v[196:197]
	v_pk_add_f32 v[190:191], v[190:191], v[198:199]
	v_cmp_lt_u32_e32 vcc, 6, v173
	s_and_b64 exec, exec, vcc
	v_lshlrev_b32_e32 v198, 16, v68
	v_and_b32_e32 v199, 0xffff0000, v68
	v_lshlrev_b32_e32 v196, 16, v69
	v_and_b32_e32 v197, 0xffff0000, v69
	v_lshlrev_b32_e32 v194, 16, v70
	v_and_b32_e32 v195, 0xffff0000, v70
	v_lshlrev_b32_e32 v192, 16, v71
	v_and_b32_e32 v193, 0xffff0000, v71
	v_pk_add_f32 v[184:185], v[184:185], v[192:193]
	v_pk_add_f32 v[186:187], v[186:187], v[194:195]
	v_pk_add_f32 v[188:189], v[188:189], v[196:197]
	v_pk_add_f32 v[190:191], v[190:191], v[198:199]
	v_cmp_lt_u32_e32 vcc, 7, v173
	s_and_b64 exec, exec, vcc
	v_lshlrev_b32_e32 v198, 16, v72
	v_and_b32_e32 v199, 0xffff0000, v72
	v_lshlrev_b32_e32 v196, 16, v73
	v_and_b32_e32 v197, 0xffff0000, v73
	v_lshlrev_b32_e32 v194, 16, v74
	v_and_b32_e32 v195, 0xffff0000, v74
	v_lshlrev_b32_e32 v192, 16, v75
	v_and_b32_e32 v193, 0xffff0000, v75
	v_pk_add_f32 v[184:185], v[184:185], v[192:193]
	v_pk_add_f32 v[186:187], v[186:187], v[194:195]
	v_pk_add_f32 v[188:189], v[188:189], v[196:197]
	v_pk_add_f32 v[190:191], v[190:191], v[198:199]
	v_cmp_lt_u32_e32 vcc, 8, v173
	s_and_b64 exec, exec, vcc
	v_lshlrev_b32_e32 v198, 16, v76
	v_and_b32_e32 v199, 0xffff0000, v76
	v_lshlrev_b32_e32 v196, 16, v77
	v_and_b32_e32 v197, 0xffff0000, v77
	v_lshlrev_b32_e32 v194, 16, v78
	v_and_b32_e32 v195, 0xffff0000, v78
	v_lshlrev_b32_e32 v192, 16, v79
	v_and_b32_e32 v193, 0xffff0000, v79
	v_pk_add_f32 v[184:185], v[184:185], v[192:193]
	v_pk_add_f32 v[186:187], v[186:187], v[194:195]
	v_pk_add_f32 v[188:189], v[188:189], v[196:197]
	v_pk_add_f32 v[190:191], v[190:191], v[198:199]
	v_cmp_lt_u32_e32 vcc, 9, v173
	s_and_b64 exec, exec, vcc
	v_lshlrev_b32_e32 v198, 16, v80
	v_and_b32_e32 v199, 0xffff0000, v80
	v_lshlrev_b32_e32 v196, 16, v81
	v_and_b32_e32 v197, 0xffff0000, v81
	v_lshlrev_b32_e32 v194, 16, v82
	v_and_b32_e32 v195, 0xffff0000, v82
	v_lshlrev_b32_e32 v192, 16, v83
	v_and_b32_e32 v193, 0xffff0000, v83
	v_pk_add_f32 v[184:185], v[184:185], v[192:193]
	v_pk_add_f32 v[186:187], v[186:187], v[194:195]
	v_pk_add_f32 v[188:189], v[188:189], v[196:197]
	v_pk_add_f32 v[190:191], v[190:191], v[198:199]
	v_cmp_lt_u32_e32 vcc, 10, v173
	s_and_b64 exec, exec, vcc
	v_lshlrev_b32_e32 v198, 16, v84
	v_and_b32_e32 v199, 0xffff0000, v84
	v_lshlrev_b32_e32 v196, 16, v85
	v_and_b32_e32 v197, 0xffff0000, v85
	v_lshlrev_b32_e32 v194, 16, v86
	v_and_b32_e32 v195, 0xffff0000, v86
	v_lshlrev_b32_e32 v192, 16, v87
	v_and_b32_e32 v193, 0xffff0000, v87
	v_pk_add_f32 v[184:185], v[184:185], v[192:193]
	v_pk_add_f32 v[186:187], v[186:187], v[194:195]
	v_pk_add_f32 v[188:189], v[188:189], v[196:197]
	v_pk_add_f32 v[190:191], v[190:191], v[198:199]
	v_cmp_lt_u32_e32 vcc, 11, v173
	s_and_b64 exec, exec, vcc
	v_lshlrev_b32_e32 v198, 16, v88
	v_and_b32_e32 v199, 0xffff0000, v88
	v_lshlrev_b32_e32 v196, 16, v89
	v_and_b32_e32 v197, 0xffff0000, v89
	v_lshlrev_b32_e32 v194, 16, v90
	v_and_b32_e32 v195, 0xffff0000, v90
	v_lshlrev_b32_e32 v192, 16, v91
	v_and_b32_e32 v193, 0xffff0000, v91
	v_pk_add_f32 v[184:185], v[184:185], v[192:193]
	v_pk_add_f32 v[186:187], v[186:187], v[194:195]
	v_pk_add_f32 v[188:189], v[188:189], v[196:197]
	v_pk_add_f32 v[190:191], v[190:191], v[198:199]
	v_cmp_lt_u32_e32 vcc, 12, v173
	s_and_b64 exec, exec, vcc
	v_lshlrev_b32_e32 v198, 16, v92
	v_and_b32_e32 v199, 0xffff0000, v92
	v_lshlrev_b32_e32 v196, 16, v93
	v_and_b32_e32 v197, 0xffff0000, v93
	v_lshlrev_b32_e32 v194, 16, v94
	v_and_b32_e32 v195, 0xffff0000, v94
	v_lshlrev_b32_e32 v192, 16, v95
	v_and_b32_e32 v193, 0xffff0000, v95
	v_pk_add_f32 v[184:185], v[184:185], v[192:193]
	v_pk_add_f32 v[186:187], v[186:187], v[194:195]
	v_pk_add_f32 v[188:189], v[188:189], v[196:197]
	v_pk_add_f32 v[190:191], v[190:191], v[198:199]
	v_cmp_lt_u32_e32 vcc, 13, v173
	s_and_b64 exec, exec, vcc
	v_lshlrev_b32_e32 v198, 16, v96
	v_and_b32_e32 v199, 0xffff0000, v96
	v_lshlrev_b32_e32 v196, 16, v97
	v_and_b32_e32 v197, 0xffff0000, v97
	v_lshlrev_b32_e32 v194, 16, v98
	v_and_b32_e32 v195, 0xffff0000, v98
	v_lshlrev_b32_e32 v192, 16, v99
	v_and_b32_e32 v193, 0xffff0000, v99
	v_pk_add_f32 v[184:185], v[184:185], v[192:193]
	v_pk_add_f32 v[186:187], v[186:187], v[194:195]
	v_pk_add_f32 v[188:189], v[188:189], v[196:197]
	v_pk_add_f32 v[190:191], v[190:191], v[198:199]
	v_cmp_lt_u32_e32 vcc, 14, v173
	s_and_b64 exec, exec, vcc
	v_lshlrev_b32_e32 v198, 16, v100
	v_and_b32_e32 v199, 0xffff0000, v100
	v_lshlrev_b32_e32 v196, 16, v101
	v_and_b32_e32 v197, 0xffff0000, v101
	v_lshlrev_b32_e32 v194, 16, v102
	v_and_b32_e32 v195, 0xffff0000, v102
	v_lshlrev_b32_e32 v192, 16, v103
	v_and_b32_e32 v193, 0xffff0000, v103
	v_pk_add_f32 v[184:185], v[184:185], v[192:193]
	v_pk_add_f32 v[186:187], v[186:187], v[194:195]
	v_pk_add_f32 v[188:189], v[188:189], v[196:197]
	v_pk_add_f32 v[190:191], v[190:191], v[198:199]
	v_cmp_lt_u32_e32 vcc, 15, v173
	s_and_b64 exec, exec, vcc
	v_lshlrev_b32_e32 v198, 16, v104
	v_and_b32_e32 v199, 0xffff0000, v104
	v_lshlrev_b32_e32 v196, 16, v105
	v_and_b32_e32 v197, 0xffff0000, v105
	v_lshlrev_b32_e32 v194, 16, v106
	v_and_b32_e32 v195, 0xffff0000, v106
	v_lshlrev_b32_e32 v192, 16, v107
	v_and_b32_e32 v193, 0xffff0000, v107
	v_pk_add_f32 v[184:185], v[184:185], v[192:193]
	v_pk_add_f32 v[186:187], v[186:187], v[194:195]
	v_pk_add_f32 v[188:189], v[188:189], v[196:197]
	v_pk_add_f32 v[190:191], v[190:191], v[198:199]
	s_mov_b64 exec, s[26:27]
	v_pk_fma_f32 v[184:185], v[184:185], v[174:175], v[176:177] op_sel_hi:[1,0,1] neg_lo:[0,0,1] neg_hi:[0,0,1]
	v_pk_fma_f32 v[186:187], v[186:187], v[174:175], v[178:179] op_sel_hi:[1,0,1] neg_lo:[0,0,1] neg_hi:[0,0,1]
	v_pk_fma_f32 v[188:189], v[188:189], v[174:175], v[180:181] op_sel_hi:[1,0,1] neg_lo:[0,0,1] neg_hi:[0,0,1]
	v_pk_fma_f32 v[190:191], v[190:191], v[174:175], v[182:183] op_sel_hi:[1,0,1] neg_lo:[0,0,1] neg_hi:[0,0,1]
	v_cvt_pk_bf16_f32 v200, v190, v191
	v_cvt_pk_bf16_f32 v201, v188, v189
	v_cvt_pk_bf16_f32 v202, v186, v187
	v_cvt_pk_bf16_f32 v203, v184, v185
	s_lshl_b32 s21, s22, 10
	s_add_u32 s24, s88, s21
	s_addc_u32 s25, s89, 0
	global_store_dwordx4 v175, v[200:203], s[24:25]
	s_add_i32 s22, s22, 0x800
	s_add_i32 s20, s20, 0x800
	s_mov_b32 s21, s20
	s_max_i32 s21, s21, 0
	s_mul_i32 s21, s21, 0x1200
	s_add_u32 s24, s90, s21
	s_addc_u32 s25, s91, 0
	global_load_dwordx4 v[44:47], v172, s[24:25]
	s_sub_i32 s21, s20, 1
	s_max_i32 s21, s21, 0
	s_mul_i32 s21, s21, 0x1200
	s_add_u32 s24, s90, s21
	s_addc_u32 s25, s91, 0
	global_load_dwordx4 v[48:51], v172, s[24:25]
	s_sub_i32 s21, s20, 2
	s_max_i32 s21, s21, 0
	s_mul_i32 s21, s21, 0x1200
	s_add_u32 s24, s90, s21
	s_addc_u32 s25, s91, 0
	global_load_dwordx4 v[52:55], v172, s[24:25]
	s_sub_i32 s21, s20, 3
	s_max_i32 s21, s21, 0
	s_mul_i32 s21, s21, 0x1200
	s_add_u32 s24, s90, s21
	s_addc_u32 s25, s91, 0
	global_load_dwordx4 v[56:59], v172, s[24:25]
	s_sub_i32 s21, s20, 4
	s_max_i32 s21, s21, 0
	s_mul_i32 s21, s21, 0x1200
	s_add_u32 s24, s90, s21
	s_addc_u32 s25, s91, 0
	global_load_dwordx4 v[60:63], v172, s[24:25]
	s_sub_i32 s21, s20, 5
	s_max_i32 s21, s21, 0
	s_mul_i32 s21, s21, 0x1200
	s_add_u32 s24, s90, s21
	s_addc_u32 s25, s91, 0
	global_load_dwordx4 v[64:67], v172, s[24:25]
	s_sub_i32 s21, s20, 6
	s_max_i32 s21, s21, 0
	s_mul_i32 s21, s21, 0x1200
	s_add_u32 s24, s90, s21
	s_addc_u32 s25, s91, 0
	global_load_dwordx4 v[68:71], v172, s[24:25]
	s_sub_i32 s21, s20, 7
	s_max_i32 s21, s21, 0
	s_mul_i32 s21, s21, 0x1200
	s_add_u32 s24, s90, s21
	s_addc_u32 s25, s91, 0
	global_load_dwordx4 v[72:75], v172, s[24:25]
	s_sub_i32 s21, s20, 8
	s_max_i32 s21, s21, 0
	s_mul_i32 s21, s21, 0x1200
	s_add_u32 s24, s90, s21
	s_addc_u32 s25, s91, 0
	global_load_dwordx4 v[76:79], v172, s[24:25]
	s_sub_i32 s21, s20, 9
	s_max_i32 s21, s21, 0
	s_mul_i32 s21, s21, 0x1200
	s_add_u32 s24, s90, s21
	s_addc_u32 s25, s91, 0
	global_load_dwordx4 v[80:83], v172, s[24:25]
	s_sub_i32 s21, s20, 10
	s_max_i32 s21, s21, 0
	s_mul_i32 s21, s21, 0x1200
	s_add_u32 s24, s90, s21
	s_addc_u32 s25, s91, 0
	global_load_dwordx4 v[84:87], v172, s[24:25]
	s_sub_i32 s21, s20, 11
	s_max_i32 s21, s21, 0
	s_mul_i32 s21, s21, 0x1200
	s_add_u32 s24, s90, s21
	s_addc_u32 s25, s91, 0
	global_load_dwordx4 v[88:91], v172, s[24:25]
	s_sub_i32 s21, s20, 12
	s_max_i32 s21, s21, 0
	s_mul_i32 s21, s21, 0x1200
	s_add_u32 s24, s90, s21
	s_addc_u32 s25, s91, 0
	global_load_dwordx4 v[92:95], v172, s[24:25]
	s_sub_i32 s21, s20, 13
	s_max_i32 s21, s21, 0
	s_mul_i32 s21, s21, 0x1200
	s_add_u32 s24, s90, s21
	s_addc_u32 s25, s91, 0
	global_load_dwordx4 v[96:99], v172, s[24:25]
	s_sub_i32 s21, s20, 14
	s_max_i32 s21, s21, 0
	s_mul_i32 s21, s21, 0x1200
	s_add_u32 s24, s90, s21
	s_addc_u32 s25, s91, 0
	global_load_dwordx4 v[100:103], v172, s[24:25]
	s_sub_i32 s21, s20, 15
	s_max_i32 s21, s21, 0
	s_mul_i32 s21, s21, 0x1200
	s_add_u32 s24, s90, s21
	s_addc_u32 s25, s91, 0
	global_load_dwordx4 v[104:107], v172, s[24:25]
	s_waitcnt vmcnt(17)
	v_lshlrev_b32_e32 v182, 16, v108
	v_and_b32_e32 v183, 0xffff0000, v108
	v_lshlrev_b32_e32 v180, 16, v109
	v_and_b32_e32 v181, 0xffff0000, v109
	v_lshlrev_b32_e32 v178, 16, v110
	v_and_b32_e32 v179, 0xffff0000, v110
	v_lshlrev_b32_e32 v176, 16, v111
	v_and_b32_e32 v177, 0xffff0000, v111
	v_mov_b32_e32 v184, v176
	v_mov_b32_e32 v185, v177
	v_mov_b32_e32 v186, v178
	v_mov_b32_e32 v187, v179
	v_mov_b32_e32 v188, v180
	v_mov_b32_e32 v189, v181
	v_mov_b32_e32 v190, v182
	v_mov_b32_e32 v191, v183
	s_mov_b64 s[26:27], exec
	v_cmp_lt_u32_e32 vcc, 1, v173
	s_and_b64 exec, exec, vcc
	v_lshlrev_b32_e32 v198, 16, v112
	v_and_b32_e32 v199, 0xffff0000, v112
	v_lshlrev_b32_e32 v196, 16, v113
	v_and_b32_e32 v197, 0xffff0000, v113
	v_lshlrev_b32_e32 v194, 16, v114
	v_and_b32_e32 v195, 0xffff0000, v114
	v_lshlrev_b32_e32 v192, 16, v115
	v_and_b32_e32 v193, 0xffff0000, v115
	v_pk_add_f32 v[184:185], v[184:185], v[192:193]
	v_pk_add_f32 v[186:187], v[186:187], v[194:195]
	v_pk_add_f32 v[188:189], v[188:189], v[196:197]
	v_pk_add_f32 v[190:191], v[190:191], v[198:199]
	v_cmp_lt_u32_e32 vcc, 2, v173
	s_and_b64 exec, exec, vcc
	v_lshlrev_b32_e32 v198, 16, v116
	v_and_b32_e32 v199, 0xffff0000, v116
	v_lshlrev_b32_e32 v196, 16, v117
	v_and_b32_e32 v197, 0xffff0000, v117
	v_lshlrev_b32_e32 v194, 16, v118
	v_and_b32_e32 v195, 0xffff0000, v118
	v_lshlrev_b32_e32 v192, 16, v119
	v_and_b32_e32 v193, 0xffff0000, v119
	v_pk_add_f32 v[184:185], v[184:185], v[192:193]
	v_pk_add_f32 v[186:187], v[186:187], v[194:195]
	v_pk_add_f32 v[188:189], v[188:189], v[196:197]
	v_pk_add_f32 v[190:191], v[190:191], v[198:199]
	v_cmp_lt_u32_e32 vcc, 3, v173
	s_and_b64 exec, exec, vcc
	v_lshlrev_b32_e32 v198, 16, v120
	v_and_b32_e32 v199, 0xffff0000, v120
	v_lshlrev_b32_e32 v196, 16, v121
	v_and_b32_e32 v197, 0xffff0000, v121
	v_lshlrev_b32_e32 v194, 16, v122
	v_and_b32_e32 v195, 0xffff0000, v122
	v_lshlrev_b32_e32 v192, 16, v123
	v_and_b32_e32 v193, 0xffff0000, v123
	v_pk_add_f32 v[184:185], v[184:185], v[192:193]
	v_pk_add_f32 v[186:187], v[186:187], v[194:195]
	v_pk_add_f32 v[188:189], v[188:189], v[196:197]
	v_pk_add_f32 v[190:191], v[190:191], v[198:199]
	v_cmp_lt_u32_e32 vcc, 4, v173
	s_and_b64 exec, exec, vcc
	v_lshlrev_b32_e32 v198, 16, v124
	v_and_b32_e32 v199, 0xffff0000, v124
	v_lshlrev_b32_e32 v196, 16, v125
	v_and_b32_e32 v197, 0xffff0000, v125
	v_lshlrev_b32_e32 v194, 16, v126
	v_and_b32_e32 v195, 0xffff0000, v126
	v_lshlrev_b32_e32 v192, 16, v127
	v_and_b32_e32 v193, 0xffff0000, v127
	v_pk_add_f32 v[184:185], v[184:185], v[192:193]
	v_pk_add_f32 v[186:187], v[186:187], v[194:195]
	v_pk_add_f32 v[188:189], v[188:189], v[196:197]
	v_pk_add_f32 v[190:191], v[190:191], v[198:199]
	v_cmp_lt_u32_e32 vcc, 5, v173
	s_and_b64 exec, exec, vcc
	v_lshlrev_b32_e32 v198, 16, v128
	v_and_b32_e32 v199, 0xffff0000, v128
	v_lshlrev_b32_e32 v196, 16, v129
	v_and_b32_e32 v197, 0xffff0000, v129
	v_lshlrev_b32_e32 v194, 16, v130
	v_and_b32_e32 v195, 0xffff0000, v130
	v_lshlrev_b32_e32 v192, 16, v131
	v_and_b32_e32 v193, 0xffff0000, v131
	v_pk_add_f32 v[184:185], v[184:185], v[192:193]
	v_pk_add_f32 v[186:187], v[186:187], v[194:195]
	v_pk_add_f32 v[188:189], v[188:189], v[196:197]
	v_pk_add_f32 v[190:191], v[190:191], v[198:199]
	v_cmp_lt_u32_e32 vcc, 6, v173
	s_and_b64 exec, exec, vcc
	v_lshlrev_b32_e32 v198, 16, v132
	v_and_b32_e32 v199, 0xffff0000, v132
	v_lshlrev_b32_e32 v196, 16, v133
	v_and_b32_e32 v197, 0xffff0000, v133
	v_lshlrev_b32_e32 v194, 16, v134
	v_and_b32_e32 v195, 0xffff0000, v134
	v_lshlrev_b32_e32 v192, 16, v135
	v_and_b32_e32 v193, 0xffff0000, v135
	v_pk_add_f32 v[184:185], v[184:185], v[192:193]
	v_pk_add_f32 v[186:187], v[186:187], v[194:195]
	v_pk_add_f32 v[188:189], v[188:189], v[196:197]
	v_pk_add_f32 v[190:191], v[190:191], v[198:199]
	v_cmp_lt_u32_e32 vcc, 7, v173
	s_and_b64 exec, exec, vcc
	v_lshlrev_b32_e32 v198, 16, v136
	v_and_b32_e32 v199, 0xffff0000, v136
	v_lshlrev_b32_e32 v196, 16, v137
	v_and_b32_e32 v197, 0xffff0000, v137
	v_lshlrev_b32_e32 v194, 16, v138
	v_and_b32_e32 v195, 0xffff0000, v138
	v_lshlrev_b32_e32 v192, 16, v139
	v_and_b32_e32 v193, 0xffff0000, v139
	v_pk_add_f32 v[184:185], v[184:185], v[192:193]
	v_pk_add_f32 v[186:187], v[186:187], v[194:195]
	v_pk_add_f32 v[188:189], v[188:189], v[196:197]
	v_pk_add_f32 v[190:191], v[190:191], v[198:199]
	v_cmp_lt_u32_e32 vcc, 8, v173
	s_and_b64 exec, exec, vcc
	v_lshlrev_b32_e32 v198, 16, v140
	v_and_b32_e32 v199, 0xffff0000, v140
	v_lshlrev_b32_e32 v196, 16, v141
	v_and_b32_e32 v197, 0xffff0000, v141
	v_lshlrev_b32_e32 v194, 16, v142
	v_and_b32_e32 v195, 0xffff0000, v142
	v_lshlrev_b32_e32 v192, 16, v143
	v_and_b32_e32 v193, 0xffff0000, v143
	v_pk_add_f32 v[184:185], v[184:185], v[192:193]
	v_pk_add_f32 v[186:187], v[186:187], v[194:195]
	v_pk_add_f32 v[188:189], v[188:189], v[196:197]
	v_pk_add_f32 v[190:191], v[190:191], v[198:199]
	v_cmp_lt_u32_e32 vcc, 9, v173
	s_and_b64 exec, exec, vcc
	v_lshlrev_b32_e32 v198, 16, v144
	v_and_b32_e32 v199, 0xffff0000, v144
	v_lshlrev_b32_e32 v196, 16, v145
	v_and_b32_e32 v197, 0xffff0000, v145
	v_lshlrev_b32_e32 v194, 16, v146
	v_and_b32_e32 v195, 0xffff0000, v146
	v_lshlrev_b32_e32 v192, 16, v147
	v_and_b32_e32 v193, 0xffff0000, v147
	v_pk_add_f32 v[184:185], v[184:185], v[192:193]
	v_pk_add_f32 v[186:187], v[186:187], v[194:195]
	v_pk_add_f32 v[188:189], v[188:189], v[196:197]
	v_pk_add_f32 v[190:191], v[190:191], v[198:199]
	v_cmp_lt_u32_e32 vcc, 10, v173
	s_and_b64 exec, exec, vcc
	v_lshlrev_b32_e32 v198, 16, v148
	v_and_b32_e32 v199, 0xffff0000, v148
	v_lshlrev_b32_e32 v196, 16, v149
	v_and_b32_e32 v197, 0xffff0000, v149
	v_lshlrev_b32_e32 v194, 16, v150
	v_and_b32_e32 v195, 0xffff0000, v150
	v_lshlrev_b32_e32 v192, 16, v151
	v_and_b32_e32 v193, 0xffff0000, v151
	v_pk_add_f32 v[184:185], v[184:185], v[192:193]
	v_pk_add_f32 v[186:187], v[186:187], v[194:195]
	v_pk_add_f32 v[188:189], v[188:189], v[196:197]
	v_pk_add_f32 v[190:191], v[190:191], v[198:199]
	v_cmp_lt_u32_e32 vcc, 11, v173
	s_and_b64 exec, exec, vcc
	v_lshlrev_b32_e32 v198, 16, v152
	v_and_b32_e32 v199, 0xffff0000, v152
	v_lshlrev_b32_e32 v196, 16, v153
	v_and_b32_e32 v197, 0xffff0000, v153
	v_lshlrev_b32_e32 v194, 16, v154
	v_and_b32_e32 v195, 0xffff0000, v154
	v_lshlrev_b32_e32 v192, 16, v155
	v_and_b32_e32 v193, 0xffff0000, v155
	v_pk_add_f32 v[184:185], v[184:185], v[192:193]
	v_pk_add_f32 v[186:187], v[186:187], v[194:195]
	v_pk_add_f32 v[188:189], v[188:189], v[196:197]
	v_pk_add_f32 v[190:191], v[190:191], v[198:199]
	v_cmp_lt_u32_e32 vcc, 12, v173
	s_and_b64 exec, exec, vcc
	v_lshlrev_b32_e32 v198, 16, v156
	v_and_b32_e32 v199, 0xffff0000, v156
	v_lshlrev_b32_e32 v196, 16, v157
	v_and_b32_e32 v197, 0xffff0000, v157
	v_lshlrev_b32_e32 v194, 16, v158
	v_and_b32_e32 v195, 0xffff0000, v158
	v_lshlrev_b32_e32 v192, 16, v159
	v_and_b32_e32 v193, 0xffff0000, v159
	v_pk_add_f32 v[184:185], v[184:185], v[192:193]
	v_pk_add_f32 v[186:187], v[186:187], v[194:195]
	v_pk_add_f32 v[188:189], v[188:189], v[196:197]
	v_pk_add_f32 v[190:191], v[190:191], v[198:199]
	v_cmp_lt_u32_e32 vcc, 13, v173
	s_and_b64 exec, exec, vcc
	v_lshlrev_b32_e32 v198, 16, v160
	v_and_b32_e32 v199, 0xffff0000, v160
	v_lshlrev_b32_e32 v196, 16, v161
	v_and_b32_e32 v197, 0xffff0000, v161
	v_lshlrev_b32_e32 v194, 16, v162
	v_and_b32_e32 v195, 0xffff0000, v162
	v_lshlrev_b32_e32 v192, 16, v163
	v_and_b32_e32 v193, 0xffff0000, v163
	v_pk_add_f32 v[184:185], v[184:185], v[192:193]
	v_pk_add_f32 v[186:187], v[186:187], v[194:195]
	v_pk_add_f32 v[188:189], v[188:189], v[196:197]
	v_pk_add_f32 v[190:191], v[190:191], v[198:199]
	v_cmp_lt_u32_e32 vcc, 14, v173
	s_and_b64 exec, exec, vcc
	v_lshlrev_b32_e32 v198, 16, v164
	v_and_b32_e32 v199, 0xffff0000, v164
	v_lshlrev_b32_e32 v196, 16, v165
	v_and_b32_e32 v197, 0xffff0000, v165
	v_lshlrev_b32_e32 v194, 16, v166
	v_and_b32_e32 v195, 0xffff0000, v166
	v_lshlrev_b32_e32 v192, 16, v167
	v_and_b32_e32 v193, 0xffff0000, v167
	v_pk_add_f32 v[184:185], v[184:185], v[192:193]
	v_pk_add_f32 v[186:187], v[186:187], v[194:195]
	v_pk_add_f32 v[188:189], v[188:189], v[196:197]
	v_pk_add_f32 v[190:191], v[190:191], v[198:199]
	v_cmp_lt_u32_e32 vcc, 15, v173
	s_and_b64 exec, exec, vcc
	v_lshlrev_b32_e32 v198, 16, v168
	v_and_b32_e32 v199, 0xffff0000, v168
	v_lshlrev_b32_e32 v196, 16, v169
	v_and_b32_e32 v197, 0xffff0000, v169
	v_lshlrev_b32_e32 v194, 16, v170
	v_and_b32_e32 v195, 0xffff0000, v170
	v_lshlrev_b32_e32 v192, 16, v171
	v_and_b32_e32 v193, 0xffff0000, v171
	v_pk_add_f32 v[184:185], v[184:185], v[192:193]
	v_pk_add_f32 v[186:187], v[186:187], v[194:195]
	v_pk_add_f32 v[188:189], v[188:189], v[196:197]
	v_pk_add_f32 v[190:191], v[190:191], v[198:199]
	s_mov_b64 exec, s[26:27]
	v_pk_fma_f32 v[184:185], v[184:185], v[174:175], v[176:177] op_sel_hi:[1,0,1] neg_lo:[0,0,1] neg_hi:[0,0,1]
	v_pk_fma_f32 v[186:187], v[186:187], v[174:175], v[178:179] op_sel_hi:[1,0,1] neg_lo:[0,0,1] neg_hi:[0,0,1]
	v_pk_fma_f32 v[188:189], v[188:189], v[174:175], v[180:181] op_sel_hi:[1,0,1] neg_lo:[0,0,1] neg_hi:[0,0,1]
	v_pk_fma_f32 v[190:191], v[190:191], v[174:175], v[182:183] op_sel_hi:[1,0,1] neg_lo:[0,0,1] neg_hi:[0,0,1]
	v_cvt_pk_bf16_f32 v200, v190, v191
	v_cvt_pk_bf16_f32 v201, v188, v189
	v_cvt_pk_bf16_f32 v202, v186, v187
	v_cvt_pk_bf16_f32 v203, v184, v185
	s_lshl_b32 s21, s22, 10
	s_add_u32 s24, s88, s21
	s_addc_u32 s25, s89, 0
	global_store_dwordx4 v175, v[200:203], s[24:25]
	s_add_i32 s22, s22, 0x800
	s_add_i32 s20, s20, 0x800
	s_mov_b32 s21, s20
	s_max_i32 s21, s21, 0
	s_mul_i32 s21, s21, 0x1200
	s_add_u32 s24, s90, s21
	s_addc_u32 s25, s91, 0
	global_load_dwordx4 v[108:111], v172, s[24:25]
	s_sub_i32 s21, s20, 1
	s_max_i32 s21, s21, 0
	s_mul_i32 s21, s21, 0x1200
	s_add_u32 s24, s90, s21
	s_addc_u32 s25, s91, 0
	global_load_dwordx4 v[112:115], v172, s[24:25]
	s_sub_i32 s21, s20, 2
	s_max_i32 s21, s21, 0
	s_mul_i32 s21, s21, 0x1200
	s_add_u32 s24, s90, s21
	s_addc_u32 s25, s91, 0
	global_load_dwordx4 v[116:119], v172, s[24:25]
	s_sub_i32 s21, s20, 3
	s_max_i32 s21, s21, 0
	s_mul_i32 s21, s21, 0x1200
	s_add_u32 s24, s90, s21
	s_addc_u32 s25, s91, 0
	global_load_dwordx4 v[120:123], v172, s[24:25]
	s_sub_i32 s21, s20, 4
	s_max_i32 s21, s21, 0
	s_mul_i32 s21, s21, 0x1200
	s_add_u32 s24, s90, s21
	s_addc_u32 s25, s91, 0
	global_load_dwordx4 v[124:127], v172, s[24:25]
	s_sub_i32 s21, s20, 5
	s_max_i32 s21, s21, 0
	s_mul_i32 s21, s21, 0x1200
	s_add_u32 s24, s90, s21
	s_addc_u32 s25, s91, 0
	global_load_dwordx4 v[128:131], v172, s[24:25]
	s_sub_i32 s21, s20, 6
	s_max_i32 s21, s21, 0
	s_mul_i32 s21, s21, 0x1200
	s_add_u32 s24, s90, s21
	s_addc_u32 s25, s91, 0
	global_load_dwordx4 v[132:135], v172, s[24:25]
	s_sub_i32 s21, s20, 7
	s_max_i32 s21, s21, 0
	s_mul_i32 s21, s21, 0x1200
	s_add_u32 s24, s90, s21
	s_addc_u32 s25, s91, 0
	global_load_dwordx4 v[136:139], v172, s[24:25]
	s_sub_i32 s21, s20, 8
	s_max_i32 s21, s21, 0
	s_mul_i32 s21, s21, 0x1200
	s_add_u32 s24, s90, s21
	s_addc_u32 s25, s91, 0
	global_load_dwordx4 v[140:143], v172, s[24:25]
	s_sub_i32 s21, s20, 9
	s_max_i32 s21, s21, 0
	s_mul_i32 s21, s21, 0x1200
	s_add_u32 s24, s90, s21
	s_addc_u32 s25, s91, 0
	global_load_dwordx4 v[144:147], v172, s[24:25]
	s_sub_i32 s21, s20, 10
	s_max_i32 s21, s21, 0
	s_mul_i32 s21, s21, 0x1200
	s_add_u32 s24, s90, s21
	s_addc_u32 s25, s91, 0
	global_load_dwordx4 v[148:151], v172, s[24:25]
	s_sub_i32 s21, s20, 11
	s_max_i32 s21, s21, 0
	s_mul_i32 s21, s21, 0x1200
	s_add_u32 s24, s90, s21
	s_addc_u32 s25, s91, 0
	global_load_dwordx4 v[152:155], v172, s[24:25]
	s_sub_i32 s21, s20, 12
	s_max_i32 s21, s21, 0
	s_mul_i32 s21, s21, 0x1200
	s_add_u32 s24, s90, s21
	s_addc_u32 s25, s91, 0
	global_load_dwordx4 v[156:159], v172, s[24:25]
	s_sub_i32 s21, s20, 13
	s_max_i32 s21, s21, 0
	s_mul_i32 s21, s21, 0x1200
	s_add_u32 s24, s90, s21
	s_addc_u32 s25, s91, 0
	global_load_dwordx4 v[160:163], v172, s[24:25]
	s_sub_i32 s21, s20, 14
	s_max_i32 s21, s21, 0
	s_mul_i32 s21, s21, 0x1200
	s_add_u32 s24, s90, s21
	s_addc_u32 s25, s91, 0
	global_load_dwordx4 v[164:167], v172, s[24:25]
	s_sub_i32 s21, s20, 15
	s_max_i32 s21, s21, 0
	s_mul_i32 s21, s21, 0x1200
	s_add_u32 s24, s90, s21
	s_addc_u32 s25, s91, 0
	global_load_dwordx4 v[168:171], v172, s[24:25]
	s_waitcnt vmcnt(17)
	v_lshlrev_b32_e32 v182, 16, v44
	v_and_b32_e32 v183, 0xffff0000, v44
	v_lshlrev_b32_e32 v180, 16, v45
	v_and_b32_e32 v181, 0xffff0000, v45
	v_lshlrev_b32_e32 v178, 16, v46
	v_and_b32_e32 v179, 0xffff0000, v46
	v_lshlrev_b32_e32 v176, 16, v47
	v_and_b32_e32 v177, 0xffff0000, v47
	v_mov_b32_e32 v184, v176
	v_mov_b32_e32 v185, v177
	v_mov_b32_e32 v186, v178
	v_mov_b32_e32 v187, v179
	v_mov_b32_e32 v188, v180
	v_mov_b32_e32 v189, v181
	v_mov_b32_e32 v190, v182
	v_mov_b32_e32 v191, v183
	s_mov_b64 s[26:27], exec
	v_cmp_lt_u32_e32 vcc, 1, v173
	s_and_b64 exec, exec, vcc
	v_lshlrev_b32_e32 v198, 16, v48
	v_and_b32_e32 v199, 0xffff0000, v48
	v_lshlrev_b32_e32 v196, 16, v49
	v_and_b32_e32 v197, 0xffff0000, v49
	v_lshlrev_b32_e32 v194, 16, v50
	v_and_b32_e32 v195, 0xffff0000, v50
	v_lshlrev_b32_e32 v192, 16, v51
	v_and_b32_e32 v193, 0xffff0000, v51
	v_pk_add_f32 v[184:185], v[184:185], v[192:193]
	v_pk_add_f32 v[186:187], v[186:187], v[194:195]
	v_pk_add_f32 v[188:189], v[188:189], v[196:197]
	v_pk_add_f32 v[190:191], v[190:191], v[198:199]
	v_cmp_lt_u32_e32 vcc, 2, v173
	s_and_b64 exec, exec, vcc
	v_lshlrev_b32_e32 v198, 16, v52
	v_and_b32_e32 v199, 0xffff0000, v52
	v_lshlrev_b32_e32 v196, 16, v53
	v_and_b32_e32 v197, 0xffff0000, v53
	v_lshlrev_b32_e32 v194, 16, v54
	v_and_b32_e32 v195, 0xffff0000, v54
	v_lshlrev_b32_e32 v192, 16, v55
	v_and_b32_e32 v193, 0xffff0000, v55
	v_pk_add_f32 v[184:185], v[184:185], v[192:193]
	v_pk_add_f32 v[186:187], v[186:187], v[194:195]
	v_pk_add_f32 v[188:189], v[188:189], v[196:197]
	v_pk_add_f32 v[190:191], v[190:191], v[198:199]
	v_cmp_lt_u32_e32 vcc, 3, v173
	s_and_b64 exec, exec, vcc
	v_lshlrev_b32_e32 v198, 16, v56
	v_and_b32_e32 v199, 0xffff0000, v56
	v_lshlrev_b32_e32 v196, 16, v57
	v_and_b32_e32 v197, 0xffff0000, v57
	v_lshlrev_b32_e32 v194, 16, v58
	v_and_b32_e32 v195, 0xffff0000, v58
	v_lshlrev_b32_e32 v192, 16, v59
	v_and_b32_e32 v193, 0xffff0000, v59
	v_pk_add_f32 v[184:185], v[184:185], v[192:193]
	v_pk_add_f32 v[186:187], v[186:187], v[194:195]
	v_pk_add_f32 v[188:189], v[188:189], v[196:197]
	v_pk_add_f32 v[190:191], v[190:191], v[198:199]
	v_cmp_lt_u32_e32 vcc, 4, v173
	s_and_b64 exec, exec, vcc
	v_lshlrev_b32_e32 v198, 16, v60
	v_and_b32_e32 v199, 0xffff0000, v60
	v_lshlrev_b32_e32 v196, 16, v61
	v_and_b32_e32 v197, 0xffff0000, v61
	v_lshlrev_b32_e32 v194, 16, v62
	v_and_b32_e32 v195, 0xffff0000, v62
	v_lshlrev_b32_e32 v192, 16, v63
	v_and_b32_e32 v193, 0xffff0000, v63
	v_pk_add_f32 v[184:185], v[184:185], v[192:193]
	v_pk_add_f32 v[186:187], v[186:187], v[194:195]
	v_pk_add_f32 v[188:189], v[188:189], v[196:197]
	v_pk_add_f32 v[190:191], v[190:191], v[198:199]
	v_cmp_lt_u32_e32 vcc, 5, v173
	s_and_b64 exec, exec, vcc
	v_lshlrev_b32_e32 v198, 16, v64
	v_and_b32_e32 v199, 0xffff0000, v64
	v_lshlrev_b32_e32 v196, 16, v65
	v_and_b32_e32 v197, 0xffff0000, v65
	v_lshlrev_b32_e32 v194, 16, v66
	v_and_b32_e32 v195, 0xffff0000, v66
	v_lshlrev_b32_e32 v192, 16, v67
	v_and_b32_e32 v193, 0xffff0000, v67
	v_pk_add_f32 v[184:185], v[184:185], v[192:193]
	v_pk_add_f32 v[186:187], v[186:187], v[194:195]
	v_pk_add_f32 v[188:189], v[188:189], v[196:197]
	v_pk_add_f32 v[190:191], v[190:191], v[198:199]
	v_cmp_lt_u32_e32 vcc, 6, v173
	s_and_b64 exec, exec, vcc
	v_lshlrev_b32_e32 v198, 16, v68
	v_and_b32_e32 v199, 0xffff0000, v68
	v_lshlrev_b32_e32 v196, 16, v69
	v_and_b32_e32 v197, 0xffff0000, v69
	v_lshlrev_b32_e32 v194, 16, v70
	v_and_b32_e32 v195, 0xffff0000, v70
	v_lshlrev_b32_e32 v192, 16, v71
	v_and_b32_e32 v193, 0xffff0000, v71
	v_pk_add_f32 v[184:185], v[184:185], v[192:193]
	v_pk_add_f32 v[186:187], v[186:187], v[194:195]
	v_pk_add_f32 v[188:189], v[188:189], v[196:197]
	v_pk_add_f32 v[190:191], v[190:191], v[198:199]
	v_cmp_lt_u32_e32 vcc, 7, v173
	s_and_b64 exec, exec, vcc
	v_lshlrev_b32_e32 v198, 16, v72
	v_and_b32_e32 v199, 0xffff0000, v72
	v_lshlrev_b32_e32 v196, 16, v73
	v_and_b32_e32 v197, 0xffff0000, v73
	v_lshlrev_b32_e32 v194, 16, v74
	v_and_b32_e32 v195, 0xffff0000, v74
	v_lshlrev_b32_e32 v192, 16, v75
	v_and_b32_e32 v193, 0xffff0000, v75
	v_pk_add_f32 v[184:185], v[184:185], v[192:193]
	v_pk_add_f32 v[186:187], v[186:187], v[194:195]
	v_pk_add_f32 v[188:189], v[188:189], v[196:197]
	v_pk_add_f32 v[190:191], v[190:191], v[198:199]
	v_cmp_lt_u32_e32 vcc, 8, v173
	s_and_b64 exec, exec, vcc
	v_lshlrev_b32_e32 v198, 16, v76
	v_and_b32_e32 v199, 0xffff0000, v76
	v_lshlrev_b32_e32 v196, 16, v77
	v_and_b32_e32 v197, 0xffff0000, v77
	v_lshlrev_b32_e32 v194, 16, v78
	v_and_b32_e32 v195, 0xffff0000, v78
	v_lshlrev_b32_e32 v192, 16, v79
	v_and_b32_e32 v193, 0xffff0000, v79
	v_pk_add_f32 v[184:185], v[184:185], v[192:193]
	v_pk_add_f32 v[186:187], v[186:187], v[194:195]
	v_pk_add_f32 v[188:189], v[188:189], v[196:197]
	v_pk_add_f32 v[190:191], v[190:191], v[198:199]
	v_cmp_lt_u32_e32 vcc, 9, v173
	s_and_b64 exec, exec, vcc
	v_lshlrev_b32_e32 v198, 16, v80
	v_and_b32_e32 v199, 0xffff0000, v80
	v_lshlrev_b32_e32 v196, 16, v81
	v_and_b32_e32 v197, 0xffff0000, v81
	v_lshlrev_b32_e32 v194, 16, v82
	v_and_b32_e32 v195, 0xffff0000, v82
	v_lshlrev_b32_e32 v192, 16, v83
	v_and_b32_e32 v193, 0xffff0000, v83
	v_pk_add_f32 v[184:185], v[184:185], v[192:193]
	v_pk_add_f32 v[186:187], v[186:187], v[194:195]
	v_pk_add_f32 v[188:189], v[188:189], v[196:197]
	v_pk_add_f32 v[190:191], v[190:191], v[198:199]
	v_cmp_lt_u32_e32 vcc, 10, v173
	s_and_b64 exec, exec, vcc
	v_lshlrev_b32_e32 v198, 16, v84
	v_and_b32_e32 v199, 0xffff0000, v84
	v_lshlrev_b32_e32 v196, 16, v85
	v_and_b32_e32 v197, 0xffff0000, v85
	v_lshlrev_b32_e32 v194, 16, v86
	v_and_b32_e32 v195, 0xffff0000, v86
	v_lshlrev_b32_e32 v192, 16, v87
	v_and_b32_e32 v193, 0xffff0000, v87
	v_pk_add_f32 v[184:185], v[184:185], v[192:193]
	v_pk_add_f32 v[186:187], v[186:187], v[194:195]
	v_pk_add_f32 v[188:189], v[188:189], v[196:197]
	v_pk_add_f32 v[190:191], v[190:191], v[198:199]
	v_cmp_lt_u32_e32 vcc, 11, v173
	s_and_b64 exec, exec, vcc
	v_lshlrev_b32_e32 v198, 16, v88
	v_and_b32_e32 v199, 0xffff0000, v88
	v_lshlrev_b32_e32 v196, 16, v89
	v_and_b32_e32 v197, 0xffff0000, v89
	v_lshlrev_b32_e32 v194, 16, v90
	v_and_b32_e32 v195, 0xffff0000, v90
	v_lshlrev_b32_e32 v192, 16, v91
	v_and_b32_e32 v193, 0xffff0000, v91
	v_pk_add_f32 v[184:185], v[184:185], v[192:193]
	v_pk_add_f32 v[186:187], v[186:187], v[194:195]
	v_pk_add_f32 v[188:189], v[188:189], v[196:197]
	v_pk_add_f32 v[190:191], v[190:191], v[198:199]
	v_cmp_lt_u32_e32 vcc, 12, v173
	s_and_b64 exec, exec, vcc
	v_lshlrev_b32_e32 v198, 16, v92
	v_and_b32_e32 v199, 0xffff0000, v92
	v_lshlrev_b32_e32 v196, 16, v93
	v_and_b32_e32 v197, 0xffff0000, v93
	v_lshlrev_b32_e32 v194, 16, v94
	v_and_b32_e32 v195, 0xffff0000, v94
	v_lshlrev_b32_e32 v192, 16, v95
	v_and_b32_e32 v193, 0xffff0000, v95
	v_pk_add_f32 v[184:185], v[184:185], v[192:193]
	v_pk_add_f32 v[186:187], v[186:187], v[194:195]
	v_pk_add_f32 v[188:189], v[188:189], v[196:197]
	v_pk_add_f32 v[190:191], v[190:191], v[198:199]
	v_cmp_lt_u32_e32 vcc, 13, v173
	s_and_b64 exec, exec, vcc
	v_lshlrev_b32_e32 v198, 16, v96
	v_and_b32_e32 v199, 0xffff0000, v96
	v_lshlrev_b32_e32 v196, 16, v97
	v_and_b32_e32 v197, 0xffff0000, v97
	v_lshlrev_b32_e32 v194, 16, v98
	v_and_b32_e32 v195, 0xffff0000, v98
	v_lshlrev_b32_e32 v192, 16, v99
	v_and_b32_e32 v193, 0xffff0000, v99
	v_pk_add_f32 v[184:185], v[184:185], v[192:193]
	v_pk_add_f32 v[186:187], v[186:187], v[194:195]
	v_pk_add_f32 v[188:189], v[188:189], v[196:197]
	v_pk_add_f32 v[190:191], v[190:191], v[198:199]
	v_cmp_lt_u32_e32 vcc, 14, v173
	s_and_b64 exec, exec, vcc
	v_lshlrev_b32_e32 v198, 16, v100
	v_and_b32_e32 v199, 0xffff0000, v100
	v_lshlrev_b32_e32 v196, 16, v101
	v_and_b32_e32 v197, 0xffff0000, v101
	v_lshlrev_b32_e32 v194, 16, v102
	v_and_b32_e32 v195, 0xffff0000, v102
	v_lshlrev_b32_e32 v192, 16, v103
	v_and_b32_e32 v193, 0xffff0000, v103
	v_pk_add_f32 v[184:185], v[184:185], v[192:193]
	v_pk_add_f32 v[186:187], v[186:187], v[194:195]
	v_pk_add_f32 v[188:189], v[188:189], v[196:197]
	v_pk_add_f32 v[190:191], v[190:191], v[198:199]
	v_cmp_lt_u32_e32 vcc, 15, v173
	s_and_b64 exec, exec, vcc
	v_lshlrev_b32_e32 v198, 16, v104
	v_and_b32_e32 v199, 0xffff0000, v104
	v_lshlrev_b32_e32 v196, 16, v105
	v_and_b32_e32 v197, 0xffff0000, v105
	v_lshlrev_b32_e32 v194, 16, v106
	v_and_b32_e32 v195, 0xffff0000, v106
	v_lshlrev_b32_e32 v192, 16, v107
	v_and_b32_e32 v193, 0xffff0000, v107
	v_pk_add_f32 v[184:185], v[184:185], v[192:193]
	v_pk_add_f32 v[186:187], v[186:187], v[194:195]
	v_pk_add_f32 v[188:189], v[188:189], v[196:197]
	v_pk_add_f32 v[190:191], v[190:191], v[198:199]
	s_mov_b64 exec, s[26:27]
	v_pk_fma_f32 v[184:185], v[184:185], v[174:175], v[176:177] op_sel_hi:[1,0,1] neg_lo:[0,0,1] neg_hi:[0,0,1]
	v_pk_fma_f32 v[186:187], v[186:187], v[174:175], v[178:179] op_sel_hi:[1,0,1] neg_lo:[0,0,1] neg_hi:[0,0,1]
	v_pk_fma_f32 v[188:189], v[188:189], v[174:175], v[180:181] op_sel_hi:[1,0,1] neg_lo:[0,0,1] neg_hi:[0,0,1]
	v_pk_fma_f32 v[190:191], v[190:191], v[174:175], v[182:183] op_sel_hi:[1,0,1] neg_lo:[0,0,1] neg_hi:[0,0,1]
	v_cvt_pk_bf16_f32 v200, v190, v191
	v_cvt_pk_bf16_f32 v201, v188, v189
	v_cvt_pk_bf16_f32 v202, v186, v187
	v_cvt_pk_bf16_f32 v203, v184, v185
	s_lshl_b32 s21, s22, 10
	s_add_u32 s24, s88, s21
	s_addc_u32 s25, s89, 0
	global_store_dwordx4 v175, v[200:203], s[24:25]
	s_add_i32 s22, s22, 0x800
	s_add_i32 s20, s20, 0x800
	s_mov_b32 s21, s20
	s_max_i32 s21, s21, 0
	s_mul_i32 s21, s21, 0x1200
	s_add_u32 s24, s90, s21
	s_addc_u32 s25, s91, 0
	global_load_dwordx4 v[44:47], v172, s[24:25]
	s_sub_i32 s21, s20, 1
	s_max_i32 s21, s21, 0
	s_mul_i32 s21, s21, 0x1200
	s_add_u32 s24, s90, s21
	s_addc_u32 s25, s91, 0
	global_load_dwordx4 v[48:51], v172, s[24:25]
	s_sub_i32 s21, s20, 2
	s_max_i32 s21, s21, 0
	s_mul_i32 s21, s21, 0x1200
	s_add_u32 s24, s90, s21
	s_addc_u32 s25, s91, 0
	global_load_dwordx4 v[52:55], v172, s[24:25]
	s_sub_i32 s21, s20, 3
	s_max_i32 s21, s21, 0
	s_mul_i32 s21, s21, 0x1200
	s_add_u32 s24, s90, s21
	s_addc_u32 s25, s91, 0
	global_load_dwordx4 v[56:59], v172, s[24:25]
	s_sub_i32 s21, s20, 4
	s_max_i32 s21, s21, 0
	s_mul_i32 s21, s21, 0x1200
	s_add_u32 s24, s90, s21
	s_addc_u32 s25, s91, 0
	global_load_dwordx4 v[60:63], v172, s[24:25]
	s_sub_i32 s21, s20, 5
	s_max_i32 s21, s21, 0
	s_mul_i32 s21, s21, 0x1200
	s_add_u32 s24, s90, s21
	s_addc_u32 s25, s91, 0
	global_load_dwordx4 v[64:67], v172, s[24:25]
	s_sub_i32 s21, s20, 6
	s_max_i32 s21, s21, 0
	s_mul_i32 s21, s21, 0x1200
	s_add_u32 s24, s90, s21
	s_addc_u32 s25, s91, 0
	global_load_dwordx4 v[68:71], v172, s[24:25]
	s_sub_i32 s21, s20, 7
	s_max_i32 s21, s21, 0
	s_mul_i32 s21, s21, 0x1200
	s_add_u32 s24, s90, s21
	s_addc_u32 s25, s91, 0
	global_load_dwordx4 v[72:75], v172, s[24:25]
	s_sub_i32 s21, s20, 8
	s_max_i32 s21, s21, 0
	s_mul_i32 s21, s21, 0x1200
	s_add_u32 s24, s90, s21
	s_addc_u32 s25, s91, 0
	global_load_dwordx4 v[76:79], v172, s[24:25]
	s_sub_i32 s21, s20, 9
	s_max_i32 s21, s21, 0
	s_mul_i32 s21, s21, 0x1200
	s_add_u32 s24, s90, s21
	s_addc_u32 s25, s91, 0
	global_load_dwordx4 v[80:83], v172, s[24:25]
	s_sub_i32 s21, s20, 10
	s_max_i32 s21, s21, 0
	s_mul_i32 s21, s21, 0x1200
	s_add_u32 s24, s90, s21
	s_addc_u32 s25, s91, 0
	global_load_dwordx4 v[84:87], v172, s[24:25]
	s_sub_i32 s21, s20, 11
	s_max_i32 s21, s21, 0
	s_mul_i32 s21, s21, 0x1200
	s_add_u32 s24, s90, s21
	s_addc_u32 s25, s91, 0
	global_load_dwordx4 v[88:91], v172, s[24:25]
	s_sub_i32 s21, s20, 12
	s_max_i32 s21, s21, 0
	s_mul_i32 s21, s21, 0x1200
	s_add_u32 s24, s90, s21
	s_addc_u32 s25, s91, 0
	global_load_dwordx4 v[92:95], v172, s[24:25]
	s_sub_i32 s21, s20, 13
	s_max_i32 s21, s21, 0
	s_mul_i32 s21, s21, 0x1200
	s_add_u32 s24, s90, s21
	s_addc_u32 s25, s91, 0
	global_load_dwordx4 v[96:99], v172, s[24:25]
	s_sub_i32 s21, s20, 14
	s_max_i32 s21, s21, 0
	s_mul_i32 s21, s21, 0x1200
	s_add_u32 s24, s90, s21
	s_addc_u32 s25, s91, 0
	global_load_dwordx4 v[100:103], v172, s[24:25]
	s_sub_i32 s21, s20, 15
	s_max_i32 s21, s21, 0
	s_mul_i32 s21, s21, 0x1200
	s_add_u32 s24, s90, s21
	s_addc_u32 s25, s91, 0
	global_load_dwordx4 v[104:107], v172, s[24:25]
	s_waitcnt vmcnt(17)
	v_lshlrev_b32_e32 v182, 16, v108
	v_and_b32_e32 v183, 0xffff0000, v108
	v_lshlrev_b32_e32 v180, 16, v109
	v_and_b32_e32 v181, 0xffff0000, v109
	v_lshlrev_b32_e32 v178, 16, v110
	v_and_b32_e32 v179, 0xffff0000, v110
	v_lshlrev_b32_e32 v176, 16, v111
	v_and_b32_e32 v177, 0xffff0000, v111
	v_mov_b32_e32 v184, v176
	v_mov_b32_e32 v185, v177
	v_mov_b32_e32 v186, v178
	v_mov_b32_e32 v187, v179
	v_mov_b32_e32 v188, v180
	v_mov_b32_e32 v189, v181
	v_mov_b32_e32 v190, v182
	v_mov_b32_e32 v191, v183
	s_mov_b64 s[26:27], exec
	v_cmp_lt_u32_e32 vcc, 1, v173
	s_and_b64 exec, exec, vcc
	v_lshlrev_b32_e32 v198, 16, v112
	v_and_b32_e32 v199, 0xffff0000, v112
	v_lshlrev_b32_e32 v196, 16, v113
	v_and_b32_e32 v197, 0xffff0000, v113
	v_lshlrev_b32_e32 v194, 16, v114
	v_and_b32_e32 v195, 0xffff0000, v114
	v_lshlrev_b32_e32 v192, 16, v115
	v_and_b32_e32 v193, 0xffff0000, v115
	v_pk_add_f32 v[184:185], v[184:185], v[192:193]
	v_pk_add_f32 v[186:187], v[186:187], v[194:195]
	v_pk_add_f32 v[188:189], v[188:189], v[196:197]
	v_pk_add_f32 v[190:191], v[190:191], v[198:199]
	v_cmp_lt_u32_e32 vcc, 2, v173
	s_and_b64 exec, exec, vcc
	v_lshlrev_b32_e32 v198, 16, v116
	v_and_b32_e32 v199, 0xffff0000, v116
	v_lshlrev_b32_e32 v196, 16, v117
	v_and_b32_e32 v197, 0xffff0000, v117
	v_lshlrev_b32_e32 v194, 16, v118
	v_and_b32_e32 v195, 0xffff0000, v118
	v_lshlrev_b32_e32 v192, 16, v119
	v_and_b32_e32 v193, 0xffff0000, v119
	v_pk_add_f32 v[184:185], v[184:185], v[192:193]
	v_pk_add_f32 v[186:187], v[186:187], v[194:195]
	v_pk_add_f32 v[188:189], v[188:189], v[196:197]
	v_pk_add_f32 v[190:191], v[190:191], v[198:199]
	v_cmp_lt_u32_e32 vcc, 3, v173
	s_and_b64 exec, exec, vcc
	v_lshlrev_b32_e32 v198, 16, v120
	v_and_b32_e32 v199, 0xffff0000, v120
	v_lshlrev_b32_e32 v196, 16, v121
	v_and_b32_e32 v197, 0xffff0000, v121
	v_lshlrev_b32_e32 v194, 16, v122
	v_and_b32_e32 v195, 0xffff0000, v122
	v_lshlrev_b32_e32 v192, 16, v123
	v_and_b32_e32 v193, 0xffff0000, v123
	v_pk_add_f32 v[184:185], v[184:185], v[192:193]
	v_pk_add_f32 v[186:187], v[186:187], v[194:195]
	v_pk_add_f32 v[188:189], v[188:189], v[196:197]
	v_pk_add_f32 v[190:191], v[190:191], v[198:199]
	v_cmp_lt_u32_e32 vcc, 4, v173
	s_and_b64 exec, exec, vcc
	v_lshlrev_b32_e32 v198, 16, v124
	v_and_b32_e32 v199, 0xffff0000, v124
	v_lshlrev_b32_e32 v196, 16, v125
	v_and_b32_e32 v197, 0xffff0000, v125
	v_lshlrev_b32_e32 v194, 16, v126
	v_and_b32_e32 v195, 0xffff0000, v126
	v_lshlrev_b32_e32 v192, 16, v127
	v_and_b32_e32 v193, 0xffff0000, v127
	v_pk_add_f32 v[184:185], v[184:185], v[192:193]
	v_pk_add_f32 v[186:187], v[186:187], v[194:195]
	v_pk_add_f32 v[188:189], v[188:189], v[196:197]
	v_pk_add_f32 v[190:191], v[190:191], v[198:199]
	v_cmp_lt_u32_e32 vcc, 5, v173
	s_and_b64 exec, exec, vcc
	v_lshlrev_b32_e32 v198, 16, v128
	v_and_b32_e32 v199, 0xffff0000, v128
	v_lshlrev_b32_e32 v196, 16, v129
	v_and_b32_e32 v197, 0xffff0000, v129
	v_lshlrev_b32_e32 v194, 16, v130
	v_and_b32_e32 v195, 0xffff0000, v130
	v_lshlrev_b32_e32 v192, 16, v131
	v_and_b32_e32 v193, 0xffff0000, v131
	v_pk_add_f32 v[184:185], v[184:185], v[192:193]
	v_pk_add_f32 v[186:187], v[186:187], v[194:195]
	v_pk_add_f32 v[188:189], v[188:189], v[196:197]
	v_pk_add_f32 v[190:191], v[190:191], v[198:199]
	v_cmp_lt_u32_e32 vcc, 6, v173
	s_and_b64 exec, exec, vcc
	v_lshlrev_b32_e32 v198, 16, v132
	v_and_b32_e32 v199, 0xffff0000, v132
	v_lshlrev_b32_e32 v196, 16, v133
	v_and_b32_e32 v197, 0xffff0000, v133
	v_lshlrev_b32_e32 v194, 16, v134
	v_and_b32_e32 v195, 0xffff0000, v134
	v_lshlrev_b32_e32 v192, 16, v135
	v_and_b32_e32 v193, 0xffff0000, v135
	v_pk_add_f32 v[184:185], v[184:185], v[192:193]
	v_pk_add_f32 v[186:187], v[186:187], v[194:195]
	v_pk_add_f32 v[188:189], v[188:189], v[196:197]
	v_pk_add_f32 v[190:191], v[190:191], v[198:199]
	v_cmp_lt_u32_e32 vcc, 7, v173
	s_and_b64 exec, exec, vcc
	v_lshlrev_b32_e32 v198, 16, v136
	v_and_b32_e32 v199, 0xffff0000, v136
	v_lshlrev_b32_e32 v196, 16, v137
	v_and_b32_e32 v197, 0xffff0000, v137
	v_lshlrev_b32_e32 v194, 16, v138
	v_and_b32_e32 v195, 0xffff0000, v138
	v_lshlrev_b32_e32 v192, 16, v139
	v_and_b32_e32 v193, 0xffff0000, v139
	v_pk_add_f32 v[184:185], v[184:185], v[192:193]
	v_pk_add_f32 v[186:187], v[186:187], v[194:195]
	v_pk_add_f32 v[188:189], v[188:189], v[196:197]
	v_pk_add_f32 v[190:191], v[190:191], v[198:199]
	v_cmp_lt_u32_e32 vcc, 8, v173
	s_and_b64 exec, exec, vcc
	v_lshlrev_b32_e32 v198, 16, v140
	v_and_b32_e32 v199, 0xffff0000, v140
	v_lshlrev_b32_e32 v196, 16, v141
	v_and_b32_e32 v197, 0xffff0000, v141
	v_lshlrev_b32_e32 v194, 16, v142
	v_and_b32_e32 v195, 0xffff0000, v142
	v_lshlrev_b32_e32 v192, 16, v143
	v_and_b32_e32 v193, 0xffff0000, v143
	v_pk_add_f32 v[184:185], v[184:185], v[192:193]
	v_pk_add_f32 v[186:187], v[186:187], v[194:195]
	v_pk_add_f32 v[188:189], v[188:189], v[196:197]
	v_pk_add_f32 v[190:191], v[190:191], v[198:199]
	v_cmp_lt_u32_e32 vcc, 9, v173
	s_and_b64 exec, exec, vcc
	v_lshlrev_b32_e32 v198, 16, v144
	v_and_b32_e32 v199, 0xffff0000, v144
	v_lshlrev_b32_e32 v196, 16, v145
	v_and_b32_e32 v197, 0xffff0000, v145
	v_lshlrev_b32_e32 v194, 16, v146
	v_and_b32_e32 v195, 0xffff0000, v146
	v_lshlrev_b32_e32 v192, 16, v147
	v_and_b32_e32 v193, 0xffff0000, v147
	v_pk_add_f32 v[184:185], v[184:185], v[192:193]
	v_pk_add_f32 v[186:187], v[186:187], v[194:195]
	v_pk_add_f32 v[188:189], v[188:189], v[196:197]
	v_pk_add_f32 v[190:191], v[190:191], v[198:199]
	v_cmp_lt_u32_e32 vcc, 10, v173
	s_and_b64 exec, exec, vcc
	v_lshlrev_b32_e32 v198, 16, v148
	v_and_b32_e32 v199, 0xffff0000, v148
	v_lshlrev_b32_e32 v196, 16, v149
	v_and_b32_e32 v197, 0xffff0000, v149
	v_lshlrev_b32_e32 v194, 16, v150
	v_and_b32_e32 v195, 0xffff0000, v150
	v_lshlrev_b32_e32 v192, 16, v151
	v_and_b32_e32 v193, 0xffff0000, v151
	v_pk_add_f32 v[184:185], v[184:185], v[192:193]
	v_pk_add_f32 v[186:187], v[186:187], v[194:195]
	v_pk_add_f32 v[188:189], v[188:189], v[196:197]
	v_pk_add_f32 v[190:191], v[190:191], v[198:199]
	v_cmp_lt_u32_e32 vcc, 11, v173
	s_and_b64 exec, exec, vcc
	v_lshlrev_b32_e32 v198, 16, v152
	v_and_b32_e32 v199, 0xffff0000, v152
	v_lshlrev_b32_e32 v196, 16, v153
	v_and_b32_e32 v197, 0xffff0000, v153
	v_lshlrev_b32_e32 v194, 16, v154
	v_and_b32_e32 v195, 0xffff0000, v154
	v_lshlrev_b32_e32 v192, 16, v155
	v_and_b32_e32 v193, 0xffff0000, v155
	v_pk_add_f32 v[184:185], v[184:185], v[192:193]
	v_pk_add_f32 v[186:187], v[186:187], v[194:195]
	v_pk_add_f32 v[188:189], v[188:189], v[196:197]
	v_pk_add_f32 v[190:191], v[190:191], v[198:199]
	v_cmp_lt_u32_e32 vcc, 12, v173
	s_and_b64 exec, exec, vcc
	v_lshlrev_b32_e32 v198, 16, v156
	v_and_b32_e32 v199, 0xffff0000, v156
	v_lshlrev_b32_e32 v196, 16, v157
	v_and_b32_e32 v197, 0xffff0000, v157
	v_lshlrev_b32_e32 v194, 16, v158
	v_and_b32_e32 v195, 0xffff0000, v158
	v_lshlrev_b32_e32 v192, 16, v159
	v_and_b32_e32 v193, 0xffff0000, v159
	v_pk_add_f32 v[184:185], v[184:185], v[192:193]
	v_pk_add_f32 v[186:187], v[186:187], v[194:195]
	v_pk_add_f32 v[188:189], v[188:189], v[196:197]
	v_pk_add_f32 v[190:191], v[190:191], v[198:199]
	v_cmp_lt_u32_e32 vcc, 13, v173
	s_and_b64 exec, exec, vcc
	v_lshlrev_b32_e32 v198, 16, v160
	v_and_b32_e32 v199, 0xffff0000, v160
	v_lshlrev_b32_e32 v196, 16, v161
	v_and_b32_e32 v197, 0xffff0000, v161
	v_lshlrev_b32_e32 v194, 16, v162
	v_and_b32_e32 v195, 0xffff0000, v162
	v_lshlrev_b32_e32 v192, 16, v163
	v_and_b32_e32 v193, 0xffff0000, v163
	v_pk_add_f32 v[184:185], v[184:185], v[192:193]
	v_pk_add_f32 v[186:187], v[186:187], v[194:195]
	v_pk_add_f32 v[188:189], v[188:189], v[196:197]
	v_pk_add_f32 v[190:191], v[190:191], v[198:199]
	v_cmp_lt_u32_e32 vcc, 14, v173
	s_and_b64 exec, exec, vcc
	v_lshlrev_b32_e32 v198, 16, v164
	v_and_b32_e32 v199, 0xffff0000, v164
	v_lshlrev_b32_e32 v196, 16, v165
	v_and_b32_e32 v197, 0xffff0000, v165
	v_lshlrev_b32_e32 v194, 16, v166
	v_and_b32_e32 v195, 0xffff0000, v166
	v_lshlrev_b32_e32 v192, 16, v167
	v_and_b32_e32 v193, 0xffff0000, v167
	v_pk_add_f32 v[184:185], v[184:185], v[192:193]
	v_pk_add_f32 v[186:187], v[186:187], v[194:195]
	v_pk_add_f32 v[188:189], v[188:189], v[196:197]
	v_pk_add_f32 v[190:191], v[190:191], v[198:199]
	v_cmp_lt_u32_e32 vcc, 15, v173
	s_and_b64 exec, exec, vcc
	v_lshlrev_b32_e32 v198, 16, v168
	v_and_b32_e32 v199, 0xffff0000, v168
	v_lshlrev_b32_e32 v196, 16, v169
	v_and_b32_e32 v197, 0xffff0000, v169
	v_lshlrev_b32_e32 v194, 16, v170
	v_and_b32_e32 v195, 0xffff0000, v170
	v_lshlrev_b32_e32 v192, 16, v171
	v_and_b32_e32 v193, 0xffff0000, v171
	v_pk_add_f32 v[184:185], v[184:185], v[192:193]
	v_pk_add_f32 v[186:187], v[186:187], v[194:195]
	v_pk_add_f32 v[188:189], v[188:189], v[196:197]
	v_pk_add_f32 v[190:191], v[190:191], v[198:199]
	s_mov_b64 exec, s[26:27]
	v_pk_fma_f32 v[184:185], v[184:185], v[174:175], v[176:177] op_sel_hi:[1,0,1] neg_lo:[0,0,1] neg_hi:[0,0,1]
	v_pk_fma_f32 v[186:187], v[186:187], v[174:175], v[178:179] op_sel_hi:[1,0,1] neg_lo:[0,0,1] neg_hi:[0,0,1]
	v_pk_fma_f32 v[188:189], v[188:189], v[174:175], v[180:181] op_sel_hi:[1,0,1] neg_lo:[0,0,1] neg_hi:[0,0,1]
	v_pk_fma_f32 v[190:191], v[190:191], v[174:175], v[182:183] op_sel_hi:[1,0,1] neg_lo:[0,0,1] neg_hi:[0,0,1]
	v_cvt_pk_bf16_f32 v200, v190, v191
	v_cvt_pk_bf16_f32 v201, v188, v189
	v_cvt_pk_bf16_f32 v202, v186, v187
	v_cvt_pk_bf16_f32 v203, v184, v185
	s_lshl_b32 s21, s22, 10
	s_add_u32 s24, s88, s21
	s_addc_u32 s25, s89, 0
	global_store_dwordx4 v175, v[200:203], s[24:25]
	s_add_i32 s22, s22, 0x800
	s_add_i32 s20, s20, 0x800
	s_mov_b32 s21, s20
	s_max_i32 s21, s21, 0
	s_mul_i32 s21, s21, 0x1200
	s_add_u32 s24, s90, s21
	s_addc_u32 s25, s91, 0
	global_load_dwordx4 v[108:111], v172, s[24:25]
	s_sub_i32 s21, s20, 1
	s_max_i32 s21, s21, 0
	s_mul_i32 s21, s21, 0x1200
	s_add_u32 s24, s90, s21
	s_addc_u32 s25, s91, 0
	global_load_dwordx4 v[112:115], v172, s[24:25]
	s_sub_i32 s21, s20, 2
	s_max_i32 s21, s21, 0
	s_mul_i32 s21, s21, 0x1200
	s_add_u32 s24, s90, s21
	s_addc_u32 s25, s91, 0
	global_load_dwordx4 v[116:119], v172, s[24:25]
	s_sub_i32 s21, s20, 3
	s_max_i32 s21, s21, 0
	s_mul_i32 s21, s21, 0x1200
	s_add_u32 s24, s90, s21
	s_addc_u32 s25, s91, 0
	global_load_dwordx4 v[120:123], v172, s[24:25]
	s_sub_i32 s21, s20, 4
	s_max_i32 s21, s21, 0
	s_mul_i32 s21, s21, 0x1200
	s_add_u32 s24, s90, s21
	s_addc_u32 s25, s91, 0
	global_load_dwordx4 v[124:127], v172, s[24:25]
	s_sub_i32 s21, s20, 5
	s_max_i32 s21, s21, 0
	s_mul_i32 s21, s21, 0x1200
	s_add_u32 s24, s90, s21
	s_addc_u32 s25, s91, 0
	global_load_dwordx4 v[128:131], v172, s[24:25]
	s_sub_i32 s21, s20, 6
	s_max_i32 s21, s21, 0
	s_mul_i32 s21, s21, 0x1200
	s_add_u32 s24, s90, s21
	s_addc_u32 s25, s91, 0
	global_load_dwordx4 v[132:135], v172, s[24:25]
	s_sub_i32 s21, s20, 7
	s_max_i32 s21, s21, 0
	s_mul_i32 s21, s21, 0x1200
	s_add_u32 s24, s90, s21
	s_addc_u32 s25, s91, 0
	global_load_dwordx4 v[136:139], v172, s[24:25]
	s_sub_i32 s21, s20, 8
	s_max_i32 s21, s21, 0
	s_mul_i32 s21, s21, 0x1200
	s_add_u32 s24, s90, s21
	s_addc_u32 s25, s91, 0
	global_load_dwordx4 v[140:143], v172, s[24:25]
	s_sub_i32 s21, s20, 9
	s_max_i32 s21, s21, 0
	s_mul_i32 s21, s21, 0x1200
	s_add_u32 s24, s90, s21
	s_addc_u32 s25, s91, 0
	global_load_dwordx4 v[144:147], v172, s[24:25]
	s_sub_i32 s21, s20, 10
	s_max_i32 s21, s21, 0
	s_mul_i32 s21, s21, 0x1200
	s_add_u32 s24, s90, s21
	s_addc_u32 s25, s91, 0
	global_load_dwordx4 v[148:151], v172, s[24:25]
	s_sub_i32 s21, s20, 11
	s_max_i32 s21, s21, 0
	s_mul_i32 s21, s21, 0x1200
	s_add_u32 s24, s90, s21
	s_addc_u32 s25, s91, 0
	global_load_dwordx4 v[152:155], v172, s[24:25]
	s_sub_i32 s21, s20, 12
	s_max_i32 s21, s21, 0
	s_mul_i32 s21, s21, 0x1200
	s_add_u32 s24, s90, s21
	s_addc_u32 s25, s91, 0
	global_load_dwordx4 v[156:159], v172, s[24:25]
	s_sub_i32 s21, s20, 13
	s_max_i32 s21, s21, 0
	s_mul_i32 s21, s21, 0x1200
	s_add_u32 s24, s90, s21
	s_addc_u32 s25, s91, 0
	global_load_dwordx4 v[160:163], v172, s[24:25]
	s_sub_i32 s21, s20, 14
	s_max_i32 s21, s21, 0
	s_mul_i32 s21, s21, 0x1200
	s_add_u32 s24, s90, s21
	s_addc_u32 s25, s91, 0
	global_load_dwordx4 v[164:167], v172, s[24:25]
	s_sub_i32 s21, s20, 15
	s_max_i32 s21, s21, 0
	s_mul_i32 s21, s21, 0x1200
	s_add_u32 s24, s90, s21
	s_addc_u32 s25, s91, 0
	global_load_dwordx4 v[168:171], v172, s[24:25]
	s_waitcnt vmcnt(17)
	v_lshlrev_b32_e32 v182, 16, v44
	v_and_b32_e32 v183, 0xffff0000, v44
	v_lshlrev_b32_e32 v180, 16, v45
	v_and_b32_e32 v181, 0xffff0000, v45
	v_lshlrev_b32_e32 v178, 16, v46
	v_and_b32_e32 v179, 0xffff0000, v46
	v_lshlrev_b32_e32 v176, 16, v47
	v_and_b32_e32 v177, 0xffff0000, v47
	v_mov_b32_e32 v184, v176
	v_mov_b32_e32 v185, v177
	v_mov_b32_e32 v186, v178
	v_mov_b32_e32 v187, v179
	v_mov_b32_e32 v188, v180
	v_mov_b32_e32 v189, v181
	v_mov_b32_e32 v190, v182
	v_mov_b32_e32 v191, v183
	s_mov_b64 s[26:27], exec
	v_cmp_lt_u32_e32 vcc, 1, v173
	s_and_b64 exec, exec, vcc
	v_lshlrev_b32_e32 v198, 16, v48
	v_and_b32_e32 v199, 0xffff0000, v48
	v_lshlrev_b32_e32 v196, 16, v49
	v_and_b32_e32 v197, 0xffff0000, v49
	v_lshlrev_b32_e32 v194, 16, v50
	v_and_b32_e32 v195, 0xffff0000, v50
	v_lshlrev_b32_e32 v192, 16, v51
	v_and_b32_e32 v193, 0xffff0000, v51
	v_pk_add_f32 v[184:185], v[184:185], v[192:193]
	v_pk_add_f32 v[186:187], v[186:187], v[194:195]
	v_pk_add_f32 v[188:189], v[188:189], v[196:197]
	v_pk_add_f32 v[190:191], v[190:191], v[198:199]
	v_cmp_lt_u32_e32 vcc, 2, v173
	s_and_b64 exec, exec, vcc
	v_lshlrev_b32_e32 v198, 16, v52
	v_and_b32_e32 v199, 0xffff0000, v52
	v_lshlrev_b32_e32 v196, 16, v53
	v_and_b32_e32 v197, 0xffff0000, v53
	v_lshlrev_b32_e32 v194, 16, v54
	v_and_b32_e32 v195, 0xffff0000, v54
	v_lshlrev_b32_e32 v192, 16, v55
	v_and_b32_e32 v193, 0xffff0000, v55
	v_pk_add_f32 v[184:185], v[184:185], v[192:193]
	v_pk_add_f32 v[186:187], v[186:187], v[194:195]
	v_pk_add_f32 v[188:189], v[188:189], v[196:197]
	v_pk_add_f32 v[190:191], v[190:191], v[198:199]
	v_cmp_lt_u32_e32 vcc, 3, v173
	s_and_b64 exec, exec, vcc
	v_lshlrev_b32_e32 v198, 16, v56
	v_and_b32_e32 v199, 0xffff0000, v56
	v_lshlrev_b32_e32 v196, 16, v57
	v_and_b32_e32 v197, 0xffff0000, v57
	v_lshlrev_b32_e32 v194, 16, v58
	v_and_b32_e32 v195, 0xffff0000, v58
	v_lshlrev_b32_e32 v192, 16, v59
	v_and_b32_e32 v193, 0xffff0000, v59
	v_pk_add_f32 v[184:185], v[184:185], v[192:193]
	v_pk_add_f32 v[186:187], v[186:187], v[194:195]
	v_pk_add_f32 v[188:189], v[188:189], v[196:197]
	v_pk_add_f32 v[190:191], v[190:191], v[198:199]
	v_cmp_lt_u32_e32 vcc, 4, v173
	s_and_b64 exec, exec, vcc
	v_lshlrev_b32_e32 v198, 16, v60
	v_and_b32_e32 v199, 0xffff0000, v60
	v_lshlrev_b32_e32 v196, 16, v61
	v_and_b32_e32 v197, 0xffff0000, v61
	v_lshlrev_b32_e32 v194, 16, v62
	v_and_b32_e32 v195, 0xffff0000, v62
	v_lshlrev_b32_e32 v192, 16, v63
	v_and_b32_e32 v193, 0xffff0000, v63
	v_pk_add_f32 v[184:185], v[184:185], v[192:193]
	v_pk_add_f32 v[186:187], v[186:187], v[194:195]
	v_pk_add_f32 v[188:189], v[188:189], v[196:197]
	v_pk_add_f32 v[190:191], v[190:191], v[198:199]
	v_cmp_lt_u32_e32 vcc, 5, v173
	s_and_b64 exec, exec, vcc
	v_lshlrev_b32_e32 v198, 16, v64
	v_and_b32_e32 v199, 0xffff0000, v64
	v_lshlrev_b32_e32 v196, 16, v65
	v_and_b32_e32 v197, 0xffff0000, v65
	v_lshlrev_b32_e32 v194, 16, v66
	v_and_b32_e32 v195, 0xffff0000, v66
	v_lshlrev_b32_e32 v192, 16, v67
	v_and_b32_e32 v193, 0xffff0000, v67
	v_pk_add_f32 v[184:185], v[184:185], v[192:193]
	v_pk_add_f32 v[186:187], v[186:187], v[194:195]
	v_pk_add_f32 v[188:189], v[188:189], v[196:197]
	v_pk_add_f32 v[190:191], v[190:191], v[198:199]
	v_cmp_lt_u32_e32 vcc, 6, v173
	s_and_b64 exec, exec, vcc
	v_lshlrev_b32_e32 v198, 16, v68
	v_and_b32_e32 v199, 0xffff0000, v68
	v_lshlrev_b32_e32 v196, 16, v69
	v_and_b32_e32 v197, 0xffff0000, v69
	v_lshlrev_b32_e32 v194, 16, v70
	v_and_b32_e32 v195, 0xffff0000, v70
	v_lshlrev_b32_e32 v192, 16, v71
	v_and_b32_e32 v193, 0xffff0000, v71
	v_pk_add_f32 v[184:185], v[184:185], v[192:193]
	v_pk_add_f32 v[186:187], v[186:187], v[194:195]
	v_pk_add_f32 v[188:189], v[188:189], v[196:197]
	v_pk_add_f32 v[190:191], v[190:191], v[198:199]
	v_cmp_lt_u32_e32 vcc, 7, v173
	s_and_b64 exec, exec, vcc
	v_lshlrev_b32_e32 v198, 16, v72
	v_and_b32_e32 v199, 0xffff0000, v72
	v_lshlrev_b32_e32 v196, 16, v73
	v_and_b32_e32 v197, 0xffff0000, v73
	v_lshlrev_b32_e32 v194, 16, v74
	v_and_b32_e32 v195, 0xffff0000, v74
	v_lshlrev_b32_e32 v192, 16, v75
	v_and_b32_e32 v193, 0xffff0000, v75
	v_pk_add_f32 v[184:185], v[184:185], v[192:193]
	v_pk_add_f32 v[186:187], v[186:187], v[194:195]
	v_pk_add_f32 v[188:189], v[188:189], v[196:197]
	v_pk_add_f32 v[190:191], v[190:191], v[198:199]
	v_cmp_lt_u32_e32 vcc, 8, v173
	s_and_b64 exec, exec, vcc
	v_lshlrev_b32_e32 v198, 16, v76
	v_and_b32_e32 v199, 0xffff0000, v76
	v_lshlrev_b32_e32 v196, 16, v77
	v_and_b32_e32 v197, 0xffff0000, v77
	v_lshlrev_b32_e32 v194, 16, v78
	v_and_b32_e32 v195, 0xffff0000, v78
	v_lshlrev_b32_e32 v192, 16, v79
	v_and_b32_e32 v193, 0xffff0000, v79
	v_pk_add_f32 v[184:185], v[184:185], v[192:193]
	v_pk_add_f32 v[186:187], v[186:187], v[194:195]
	v_pk_add_f32 v[188:189], v[188:189], v[196:197]
	v_pk_add_f32 v[190:191], v[190:191], v[198:199]
	v_cmp_lt_u32_e32 vcc, 9, v173
	s_and_b64 exec, exec, vcc
	v_lshlrev_b32_e32 v198, 16, v80
	v_and_b32_e32 v199, 0xffff0000, v80
	v_lshlrev_b32_e32 v196, 16, v81
	v_and_b32_e32 v197, 0xffff0000, v81
	v_lshlrev_b32_e32 v194, 16, v82
	v_and_b32_e32 v195, 0xffff0000, v82
	v_lshlrev_b32_e32 v192, 16, v83
	v_and_b32_e32 v193, 0xffff0000, v83
	v_pk_add_f32 v[184:185], v[184:185], v[192:193]
	v_pk_add_f32 v[186:187], v[186:187], v[194:195]
	v_pk_add_f32 v[188:189], v[188:189], v[196:197]
	v_pk_add_f32 v[190:191], v[190:191], v[198:199]
	v_cmp_lt_u32_e32 vcc, 10, v173
	s_and_b64 exec, exec, vcc
	v_lshlrev_b32_e32 v198, 16, v84
	v_and_b32_e32 v199, 0xffff0000, v84
	v_lshlrev_b32_e32 v196, 16, v85
	v_and_b32_e32 v197, 0xffff0000, v85
	v_lshlrev_b32_e32 v194, 16, v86
	v_and_b32_e32 v195, 0xffff0000, v86
	v_lshlrev_b32_e32 v192, 16, v87
	v_and_b32_e32 v193, 0xffff0000, v87
	v_pk_add_f32 v[184:185], v[184:185], v[192:193]
	v_pk_add_f32 v[186:187], v[186:187], v[194:195]
	v_pk_add_f32 v[188:189], v[188:189], v[196:197]
	v_pk_add_f32 v[190:191], v[190:191], v[198:199]
	v_cmp_lt_u32_e32 vcc, 11, v173
	s_and_b64 exec, exec, vcc
	v_lshlrev_b32_e32 v198, 16, v88
	v_and_b32_e32 v199, 0xffff0000, v88
	v_lshlrev_b32_e32 v196, 16, v89
	v_and_b32_e32 v197, 0xffff0000, v89
	v_lshlrev_b32_e32 v194, 16, v90
	v_and_b32_e32 v195, 0xffff0000, v90
	v_lshlrev_b32_e32 v192, 16, v91
	v_and_b32_e32 v193, 0xffff0000, v91
	v_pk_add_f32 v[184:185], v[184:185], v[192:193]
	v_pk_add_f32 v[186:187], v[186:187], v[194:195]
	v_pk_add_f32 v[188:189], v[188:189], v[196:197]
	v_pk_add_f32 v[190:191], v[190:191], v[198:199]
	v_cmp_lt_u32_e32 vcc, 12, v173
	s_and_b64 exec, exec, vcc
	v_lshlrev_b32_e32 v198, 16, v92
	v_and_b32_e32 v199, 0xffff0000, v92
	v_lshlrev_b32_e32 v196, 16, v93
	v_and_b32_e32 v197, 0xffff0000, v93
	v_lshlrev_b32_e32 v194, 16, v94
	v_and_b32_e32 v195, 0xffff0000, v94
	v_lshlrev_b32_e32 v192, 16, v95
	v_and_b32_e32 v193, 0xffff0000, v95
	v_pk_add_f32 v[184:185], v[184:185], v[192:193]
	v_pk_add_f32 v[186:187], v[186:187], v[194:195]
	v_pk_add_f32 v[188:189], v[188:189], v[196:197]
	v_pk_add_f32 v[190:191], v[190:191], v[198:199]
	v_cmp_lt_u32_e32 vcc, 13, v173
	s_and_b64 exec, exec, vcc
	v_lshlrev_b32_e32 v198, 16, v96
	v_and_b32_e32 v199, 0xffff0000, v96
	v_lshlrev_b32_e32 v196, 16, v97
	v_and_b32_e32 v197, 0xffff0000, v97
	v_lshlrev_b32_e32 v194, 16, v98
	v_and_b32_e32 v195, 0xffff0000, v98
	v_lshlrev_b32_e32 v192, 16, v99
	v_and_b32_e32 v193, 0xffff0000, v99
	v_pk_add_f32 v[184:185], v[184:185], v[192:193]
	v_pk_add_f32 v[186:187], v[186:187], v[194:195]
	v_pk_add_f32 v[188:189], v[188:189], v[196:197]
	v_pk_add_f32 v[190:191], v[190:191], v[198:199]
	v_cmp_lt_u32_e32 vcc, 14, v173
	s_and_b64 exec, exec, vcc
	v_lshlrev_b32_e32 v198, 16, v100
	v_and_b32_e32 v199, 0xffff0000, v100
	v_lshlrev_b32_e32 v196, 16, v101
	v_and_b32_e32 v197, 0xffff0000, v101
	v_lshlrev_b32_e32 v194, 16, v102
	v_and_b32_e32 v195, 0xffff0000, v102
	v_lshlrev_b32_e32 v192, 16, v103
	v_and_b32_e32 v193, 0xffff0000, v103
	v_pk_add_f32 v[184:185], v[184:185], v[192:193]
	v_pk_add_f32 v[186:187], v[186:187], v[194:195]
	v_pk_add_f32 v[188:189], v[188:189], v[196:197]
	v_pk_add_f32 v[190:191], v[190:191], v[198:199]
	v_cmp_lt_u32_e32 vcc, 15, v173
	s_and_b64 exec, exec, vcc
	v_lshlrev_b32_e32 v198, 16, v104
	v_and_b32_e32 v199, 0xffff0000, v104
	v_lshlrev_b32_e32 v196, 16, v105
	v_and_b32_e32 v197, 0xffff0000, v105
	v_lshlrev_b32_e32 v194, 16, v106
	v_and_b32_e32 v195, 0xffff0000, v106
	v_lshlrev_b32_e32 v192, 16, v107
	v_and_b32_e32 v193, 0xffff0000, v107
	v_pk_add_f32 v[184:185], v[184:185], v[192:193]
	v_pk_add_f32 v[186:187], v[186:187], v[194:195]
	v_pk_add_f32 v[188:189], v[188:189], v[196:197]
	v_pk_add_f32 v[190:191], v[190:191], v[198:199]
	s_mov_b64 exec, s[26:27]
	v_pk_fma_f32 v[184:185], v[184:185], v[174:175], v[176:177] op_sel_hi:[1,0,1] neg_lo:[0,0,1] neg_hi:[0,0,1]
	v_pk_fma_f32 v[186:187], v[186:187], v[174:175], v[178:179] op_sel_hi:[1,0,1] neg_lo:[0,0,1] neg_hi:[0,0,1]
	v_pk_fma_f32 v[188:189], v[188:189], v[174:175], v[180:181] op_sel_hi:[1,0,1] neg_lo:[0,0,1] neg_hi:[0,0,1]
	v_pk_fma_f32 v[190:191], v[190:191], v[174:175], v[182:183] op_sel_hi:[1,0,1] neg_lo:[0,0,1] neg_hi:[0,0,1]
	v_cvt_pk_bf16_f32 v200, v190, v191
	v_cvt_pk_bf16_f32 v201, v188, v189
	v_cvt_pk_bf16_f32 v202, v186, v187
	v_cvt_pk_bf16_f32 v203, v184, v185
	s_lshl_b32 s21, s22, 10
	s_add_u32 s24, s88, s21
	s_addc_u32 s25, s89, 0
	global_store_dwordx4 v175, v[200:203], s[24:25]
	s_add_i32 s22, s22, 0x800
	s_add_i32 s20, s20, 0x800
	s_mov_b32 s21, s20
	s_max_i32 s21, s21, 0
	s_mul_i32 s21, s21, 0x1200
	s_add_u32 s24, s90, s21
	s_addc_u32 s25, s91, 0
	global_load_dwordx4 v[44:47], v172, s[24:25]
	s_sub_i32 s21, s20, 1
	s_max_i32 s21, s21, 0
	s_mul_i32 s21, s21, 0x1200
	s_add_u32 s24, s90, s21
	s_addc_u32 s25, s91, 0
	global_load_dwordx4 v[48:51], v172, s[24:25]
	s_sub_i32 s21, s20, 2
	s_max_i32 s21, s21, 0
	s_mul_i32 s21, s21, 0x1200
	s_add_u32 s24, s90, s21
	s_addc_u32 s25, s91, 0
	global_load_dwordx4 v[52:55], v172, s[24:25]
	s_sub_i32 s21, s20, 3
	s_max_i32 s21, s21, 0
	s_mul_i32 s21, s21, 0x1200
	s_add_u32 s24, s90, s21
	s_addc_u32 s25, s91, 0
	global_load_dwordx4 v[56:59], v172, s[24:25]
	s_sub_i32 s21, s20, 4
	s_max_i32 s21, s21, 0
	s_mul_i32 s21, s21, 0x1200
	s_add_u32 s24, s90, s21
	s_addc_u32 s25, s91, 0
	global_load_dwordx4 v[60:63], v172, s[24:25]
	s_sub_i32 s21, s20, 5
	s_max_i32 s21, s21, 0
	s_mul_i32 s21, s21, 0x1200
	s_add_u32 s24, s90, s21
	s_addc_u32 s25, s91, 0
	global_load_dwordx4 v[64:67], v172, s[24:25]
	s_sub_i32 s21, s20, 6
	s_max_i32 s21, s21, 0
	s_mul_i32 s21, s21, 0x1200
	s_add_u32 s24, s90, s21
	s_addc_u32 s25, s91, 0
	global_load_dwordx4 v[68:71], v172, s[24:25]
	s_sub_i32 s21, s20, 7
	s_max_i32 s21, s21, 0
	s_mul_i32 s21, s21, 0x1200
	s_add_u32 s24, s90, s21
	s_addc_u32 s25, s91, 0
	global_load_dwordx4 v[72:75], v172, s[24:25]
	s_sub_i32 s21, s20, 8
	s_max_i32 s21, s21, 0
	s_mul_i32 s21, s21, 0x1200
	s_add_u32 s24, s90, s21
	s_addc_u32 s25, s91, 0
	global_load_dwordx4 v[76:79], v172, s[24:25]
	s_sub_i32 s21, s20, 9
	s_max_i32 s21, s21, 0
	s_mul_i32 s21, s21, 0x1200
	s_add_u32 s24, s90, s21
	s_addc_u32 s25, s91, 0
	global_load_dwordx4 v[80:83], v172, s[24:25]
	s_sub_i32 s21, s20, 10
	s_max_i32 s21, s21, 0
	s_mul_i32 s21, s21, 0x1200
	s_add_u32 s24, s90, s21
	s_addc_u32 s25, s91, 0
	global_load_dwordx4 v[84:87], v172, s[24:25]
	s_sub_i32 s21, s20, 11
	s_max_i32 s21, s21, 0
	s_mul_i32 s21, s21, 0x1200
	s_add_u32 s24, s90, s21
	s_addc_u32 s25, s91, 0
	global_load_dwordx4 v[88:91], v172, s[24:25]
	s_sub_i32 s21, s20, 12
	s_max_i32 s21, s21, 0
	s_mul_i32 s21, s21, 0x1200
	s_add_u32 s24, s90, s21
	s_addc_u32 s25, s91, 0
	global_load_dwordx4 v[92:95], v172, s[24:25]
	s_sub_i32 s21, s20, 13
	s_max_i32 s21, s21, 0
	s_mul_i32 s21, s21, 0x1200
	s_add_u32 s24, s90, s21
	s_addc_u32 s25, s91, 0
	global_load_dwordx4 v[96:99], v172, s[24:25]
	s_sub_i32 s21, s20, 14
	s_max_i32 s21, s21, 0
	s_mul_i32 s21, s21, 0x1200
	s_add_u32 s24, s90, s21
	s_addc_u32 s25, s91, 0
	global_load_dwordx4 v[100:103], v172, s[24:25]
	s_sub_i32 s21, s20, 15
	s_max_i32 s21, s21, 0
	s_mul_i32 s21, s21, 0x1200
	s_add_u32 s24, s90, s21
	s_addc_u32 s25, s91, 0
	global_load_dwordx4 v[104:107], v172, s[24:25]
	s_waitcnt vmcnt(17)
	v_lshlrev_b32_e32 v182, 16, v108
	v_and_b32_e32 v183, 0xffff0000, v108
	v_lshlrev_b32_e32 v180, 16, v109
	v_and_b32_e32 v181, 0xffff0000, v109
	v_lshlrev_b32_e32 v178, 16, v110
	v_and_b32_e32 v179, 0xffff0000, v110
	v_lshlrev_b32_e32 v176, 16, v111
	v_and_b32_e32 v177, 0xffff0000, v111
	v_mov_b32_e32 v184, v176
	v_mov_b32_e32 v185, v177
	v_mov_b32_e32 v186, v178
	v_mov_b32_e32 v187, v179
	v_mov_b32_e32 v188, v180
	v_mov_b32_e32 v189, v181
	v_mov_b32_e32 v190, v182
	v_mov_b32_e32 v191, v183
	s_mov_b64 s[26:27], exec
	v_cmp_lt_u32_e32 vcc, 1, v173
	s_and_b64 exec, exec, vcc
	v_lshlrev_b32_e32 v198, 16, v112
	v_and_b32_e32 v199, 0xffff0000, v112
	v_lshlrev_b32_e32 v196, 16, v113
	v_and_b32_e32 v197, 0xffff0000, v113
	v_lshlrev_b32_e32 v194, 16, v114
	v_and_b32_e32 v195, 0xffff0000, v114
	v_lshlrev_b32_e32 v192, 16, v115
	v_and_b32_e32 v193, 0xffff0000, v115
	v_pk_add_f32 v[184:185], v[184:185], v[192:193]
	v_pk_add_f32 v[186:187], v[186:187], v[194:195]
	v_pk_add_f32 v[188:189], v[188:189], v[196:197]
	v_pk_add_f32 v[190:191], v[190:191], v[198:199]
	v_cmp_lt_u32_e32 vcc, 2, v173
	s_and_b64 exec, exec, vcc
	v_lshlrev_b32_e32 v198, 16, v116
	v_and_b32_e32 v199, 0xffff0000, v116
	v_lshlrev_b32_e32 v196, 16, v117
	v_and_b32_e32 v197, 0xffff0000, v117
	v_lshlrev_b32_e32 v194, 16, v118
	v_and_b32_e32 v195, 0xffff0000, v118
	v_lshlrev_b32_e32 v192, 16, v119
	v_and_b32_e32 v193, 0xffff0000, v119
	v_pk_add_f32 v[184:185], v[184:185], v[192:193]
	v_pk_add_f32 v[186:187], v[186:187], v[194:195]
	v_pk_add_f32 v[188:189], v[188:189], v[196:197]
	v_pk_add_f32 v[190:191], v[190:191], v[198:199]
	v_cmp_lt_u32_e32 vcc, 3, v173
	s_and_b64 exec, exec, vcc
	v_lshlrev_b32_e32 v198, 16, v120
	v_and_b32_e32 v199, 0xffff0000, v120
	v_lshlrev_b32_e32 v196, 16, v121
	v_and_b32_e32 v197, 0xffff0000, v121
	v_lshlrev_b32_e32 v194, 16, v122
	v_and_b32_e32 v195, 0xffff0000, v122
	v_lshlrev_b32_e32 v192, 16, v123
	v_and_b32_e32 v193, 0xffff0000, v123
	v_pk_add_f32 v[184:185], v[184:185], v[192:193]
	v_pk_add_f32 v[186:187], v[186:187], v[194:195]
	v_pk_add_f32 v[188:189], v[188:189], v[196:197]
	v_pk_add_f32 v[190:191], v[190:191], v[198:199]
	v_cmp_lt_u32_e32 vcc, 4, v173
	s_and_b64 exec, exec, vcc
	v_lshlrev_b32_e32 v198, 16, v124
	v_and_b32_e32 v199, 0xffff0000, v124
	v_lshlrev_b32_e32 v196, 16, v125
	v_and_b32_e32 v197, 0xffff0000, v125
	v_lshlrev_b32_e32 v194, 16, v126
	v_and_b32_e32 v195, 0xffff0000, v126
	v_lshlrev_b32_e32 v192, 16, v127
	v_and_b32_e32 v193, 0xffff0000, v127
	v_pk_add_f32 v[184:185], v[184:185], v[192:193]
	v_pk_add_f32 v[186:187], v[186:187], v[194:195]
	v_pk_add_f32 v[188:189], v[188:189], v[196:197]
	v_pk_add_f32 v[190:191], v[190:191], v[198:199]
	v_cmp_lt_u32_e32 vcc, 5, v173
	s_and_b64 exec, exec, vcc
	v_lshlrev_b32_e32 v198, 16, v128
	v_and_b32_e32 v199, 0xffff0000, v128
	v_lshlrev_b32_e32 v196, 16, v129
	v_and_b32_e32 v197, 0xffff0000, v129
	v_lshlrev_b32_e32 v194, 16, v130
	v_and_b32_e32 v195, 0xffff0000, v130
	v_lshlrev_b32_e32 v192, 16, v131
	v_and_b32_e32 v193, 0xffff0000, v131
	v_pk_add_f32 v[184:185], v[184:185], v[192:193]
	v_pk_add_f32 v[186:187], v[186:187], v[194:195]
	v_pk_add_f32 v[188:189], v[188:189], v[196:197]
	v_pk_add_f32 v[190:191], v[190:191], v[198:199]
	v_cmp_lt_u32_e32 vcc, 6, v173
	s_and_b64 exec, exec, vcc
	v_lshlrev_b32_e32 v198, 16, v132
	v_and_b32_e32 v199, 0xffff0000, v132
	v_lshlrev_b32_e32 v196, 16, v133
	v_and_b32_e32 v197, 0xffff0000, v133
	v_lshlrev_b32_e32 v194, 16, v134
	v_and_b32_e32 v195, 0xffff0000, v134
	v_lshlrev_b32_e32 v192, 16, v135
	v_and_b32_e32 v193, 0xffff0000, v135
	v_pk_add_f32 v[184:185], v[184:185], v[192:193]
	v_pk_add_f32 v[186:187], v[186:187], v[194:195]
	v_pk_add_f32 v[188:189], v[188:189], v[196:197]
	v_pk_add_f32 v[190:191], v[190:191], v[198:199]
	v_cmp_lt_u32_e32 vcc, 7, v173
	s_and_b64 exec, exec, vcc
	v_lshlrev_b32_e32 v198, 16, v136
	v_and_b32_e32 v199, 0xffff0000, v136
	v_lshlrev_b32_e32 v196, 16, v137
	v_and_b32_e32 v197, 0xffff0000, v137
	v_lshlrev_b32_e32 v194, 16, v138
	v_and_b32_e32 v195, 0xffff0000, v138
	v_lshlrev_b32_e32 v192, 16, v139
	v_and_b32_e32 v193, 0xffff0000, v139
	v_pk_add_f32 v[184:185], v[184:185], v[192:193]
	v_pk_add_f32 v[186:187], v[186:187], v[194:195]
	v_pk_add_f32 v[188:189], v[188:189], v[196:197]
	v_pk_add_f32 v[190:191], v[190:191], v[198:199]
	v_cmp_lt_u32_e32 vcc, 8, v173
	s_and_b64 exec, exec, vcc
	v_lshlrev_b32_e32 v198, 16, v140
	v_and_b32_e32 v199, 0xffff0000, v140
	v_lshlrev_b32_e32 v196, 16, v141
	v_and_b32_e32 v197, 0xffff0000, v141
	v_lshlrev_b32_e32 v194, 16, v142
	v_and_b32_e32 v195, 0xffff0000, v142
	v_lshlrev_b32_e32 v192, 16, v143
	v_and_b32_e32 v193, 0xffff0000, v143
	v_pk_add_f32 v[184:185], v[184:185], v[192:193]
	v_pk_add_f32 v[186:187], v[186:187], v[194:195]
	v_pk_add_f32 v[188:189], v[188:189], v[196:197]
	v_pk_add_f32 v[190:191], v[190:191], v[198:199]
	v_cmp_lt_u32_e32 vcc, 9, v173
	s_and_b64 exec, exec, vcc
	v_lshlrev_b32_e32 v198, 16, v144
	v_and_b32_e32 v199, 0xffff0000, v144
	v_lshlrev_b32_e32 v196, 16, v145
	v_and_b32_e32 v197, 0xffff0000, v145
	v_lshlrev_b32_e32 v194, 16, v146
	v_and_b32_e32 v195, 0xffff0000, v146
	v_lshlrev_b32_e32 v192, 16, v147
	v_and_b32_e32 v193, 0xffff0000, v147
	v_pk_add_f32 v[184:185], v[184:185], v[192:193]
	v_pk_add_f32 v[186:187], v[186:187], v[194:195]
	v_pk_add_f32 v[188:189], v[188:189], v[196:197]
	v_pk_add_f32 v[190:191], v[190:191], v[198:199]
	v_cmp_lt_u32_e32 vcc, 10, v173
	s_and_b64 exec, exec, vcc
	v_lshlrev_b32_e32 v198, 16, v148
	v_and_b32_e32 v199, 0xffff0000, v148
	v_lshlrev_b32_e32 v196, 16, v149
	v_and_b32_e32 v197, 0xffff0000, v149
	v_lshlrev_b32_e32 v194, 16, v150
	v_and_b32_e32 v195, 0xffff0000, v150
	v_lshlrev_b32_e32 v192, 16, v151
	v_and_b32_e32 v193, 0xffff0000, v151
	v_pk_add_f32 v[184:185], v[184:185], v[192:193]
	v_pk_add_f32 v[186:187], v[186:187], v[194:195]
	v_pk_add_f32 v[188:189], v[188:189], v[196:197]
	v_pk_add_f32 v[190:191], v[190:191], v[198:199]
	v_cmp_lt_u32_e32 vcc, 11, v173
	s_and_b64 exec, exec, vcc
	v_lshlrev_b32_e32 v198, 16, v152
	v_and_b32_e32 v199, 0xffff0000, v152
	v_lshlrev_b32_e32 v196, 16, v153
	v_and_b32_e32 v197, 0xffff0000, v153
	v_lshlrev_b32_e32 v194, 16, v154
	v_and_b32_e32 v195, 0xffff0000, v154
	v_lshlrev_b32_e32 v192, 16, v155
	v_and_b32_e32 v193, 0xffff0000, v155
	v_pk_add_f32 v[184:185], v[184:185], v[192:193]
	v_pk_add_f32 v[186:187], v[186:187], v[194:195]
	v_pk_add_f32 v[188:189], v[188:189], v[196:197]
	v_pk_add_f32 v[190:191], v[190:191], v[198:199]
	v_cmp_lt_u32_e32 vcc, 12, v173
	s_and_b64 exec, exec, vcc
	v_lshlrev_b32_e32 v198, 16, v156
	v_and_b32_e32 v199, 0xffff0000, v156
	v_lshlrev_b32_e32 v196, 16, v157
	v_and_b32_e32 v197, 0xffff0000, v157
	v_lshlrev_b32_e32 v194, 16, v158
	v_and_b32_e32 v195, 0xffff0000, v158
	v_lshlrev_b32_e32 v192, 16, v159
	v_and_b32_e32 v193, 0xffff0000, v159
	v_pk_add_f32 v[184:185], v[184:185], v[192:193]
	v_pk_add_f32 v[186:187], v[186:187], v[194:195]
	v_pk_add_f32 v[188:189], v[188:189], v[196:197]
	v_pk_add_f32 v[190:191], v[190:191], v[198:199]
	v_cmp_lt_u32_e32 vcc, 13, v173
	s_and_b64 exec, exec, vcc
	v_lshlrev_b32_e32 v198, 16, v160
	v_and_b32_e32 v199, 0xffff0000, v160
	v_lshlrev_b32_e32 v196, 16, v161
	v_and_b32_e32 v197, 0xffff0000, v161
	v_lshlrev_b32_e32 v194, 16, v162
	v_and_b32_e32 v195, 0xffff0000, v162
	v_lshlrev_b32_e32 v192, 16, v163
	v_and_b32_e32 v193, 0xffff0000, v163
	v_pk_add_f32 v[184:185], v[184:185], v[192:193]
	v_pk_add_f32 v[186:187], v[186:187], v[194:195]
	v_pk_add_f32 v[188:189], v[188:189], v[196:197]
	v_pk_add_f32 v[190:191], v[190:191], v[198:199]
	v_cmp_lt_u32_e32 vcc, 14, v173
	s_and_b64 exec, exec, vcc
	v_lshlrev_b32_e32 v198, 16, v164
	v_and_b32_e32 v199, 0xffff0000, v164
	v_lshlrev_b32_e32 v196, 16, v165
	v_and_b32_e32 v197, 0xffff0000, v165
	v_lshlrev_b32_e32 v194, 16, v166
	v_and_b32_e32 v195, 0xffff0000, v166
	v_lshlrev_b32_e32 v192, 16, v167
	v_and_b32_e32 v193, 0xffff0000, v167
	v_pk_add_f32 v[184:185], v[184:185], v[192:193]
	v_pk_add_f32 v[186:187], v[186:187], v[194:195]
	v_pk_add_f32 v[188:189], v[188:189], v[196:197]
	v_pk_add_f32 v[190:191], v[190:191], v[198:199]
	v_cmp_lt_u32_e32 vcc, 15, v173
	s_and_b64 exec, exec, vcc
	v_lshlrev_b32_e32 v198, 16, v168
	v_and_b32_e32 v199, 0xffff0000, v168
	v_lshlrev_b32_e32 v196, 16, v169
	v_and_b32_e32 v197, 0xffff0000, v169
	v_lshlrev_b32_e32 v194, 16, v170
	v_and_b32_e32 v195, 0xffff0000, v170
	v_lshlrev_b32_e32 v192, 16, v171
	v_and_b32_e32 v193, 0xffff0000, v171
	v_pk_add_f32 v[184:185], v[184:185], v[192:193]
	v_pk_add_f32 v[186:187], v[186:187], v[194:195]
	v_pk_add_f32 v[188:189], v[188:189], v[196:197]
	v_pk_add_f32 v[190:191], v[190:191], v[198:199]
	s_mov_b64 exec, s[26:27]
	v_pk_fma_f32 v[184:185], v[184:185], v[174:175], v[176:177] op_sel_hi:[1,0,1] neg_lo:[0,0,1] neg_hi:[0,0,1]
	v_pk_fma_f32 v[186:187], v[186:187], v[174:175], v[178:179] op_sel_hi:[1,0,1] neg_lo:[0,0,1] neg_hi:[0,0,1]
	v_pk_fma_f32 v[188:189], v[188:189], v[174:175], v[180:181] op_sel_hi:[1,0,1] neg_lo:[0,0,1] neg_hi:[0,0,1]
	v_pk_fma_f32 v[190:191], v[190:191], v[174:175], v[182:183] op_sel_hi:[1,0,1] neg_lo:[0,0,1] neg_hi:[0,0,1]
	v_cvt_pk_bf16_f32 v200, v190, v191
	v_cvt_pk_bf16_f32 v201, v188, v189
	v_cvt_pk_bf16_f32 v202, v186, v187
	v_cvt_pk_bf16_f32 v203, v184, v185
	s_lshl_b32 s21, s22, 10
	s_add_u32 s24, s88, s21
	s_addc_u32 s25, s89, 0
	global_store_dwordx4 v175, v[200:203], s[24:25]
	s_add_i32 s22, s22, 0x800
	s_add_i32 s20, s20, 0x800
	s_mov_b32 s21, s20
	s_max_i32 s21, s21, 0
	s_mul_i32 s21, s21, 0x1200
	s_add_u32 s24, s90, s21
	s_addc_u32 s25, s91, 0
	global_load_dwordx4 v[108:111], v172, s[24:25]
	s_sub_i32 s21, s20, 1
	s_max_i32 s21, s21, 0
	s_mul_i32 s21, s21, 0x1200
	s_add_u32 s24, s90, s21
	s_addc_u32 s25, s91, 0
	global_load_dwordx4 v[112:115], v172, s[24:25]
	s_sub_i32 s21, s20, 2
	s_max_i32 s21, s21, 0
	s_mul_i32 s21, s21, 0x1200
	s_add_u32 s24, s90, s21
	s_addc_u32 s25, s91, 0
	global_load_dwordx4 v[116:119], v172, s[24:25]
	s_sub_i32 s21, s20, 3
	s_max_i32 s21, s21, 0
	s_mul_i32 s21, s21, 0x1200
	s_add_u32 s24, s90, s21
	s_addc_u32 s25, s91, 0
	global_load_dwordx4 v[120:123], v172, s[24:25]
	s_sub_i32 s21, s20, 4
	s_max_i32 s21, s21, 0
	s_mul_i32 s21, s21, 0x1200
	s_add_u32 s24, s90, s21
	s_addc_u32 s25, s91, 0
	global_load_dwordx4 v[124:127], v172, s[24:25]
	s_sub_i32 s21, s20, 5
	s_max_i32 s21, s21, 0
	s_mul_i32 s21, s21, 0x1200
	s_add_u32 s24, s90, s21
	s_addc_u32 s25, s91, 0
	global_load_dwordx4 v[128:131], v172, s[24:25]
	s_sub_i32 s21, s20, 6
	s_max_i32 s21, s21, 0
	s_mul_i32 s21, s21, 0x1200
	s_add_u32 s24, s90, s21
	s_addc_u32 s25, s91, 0
	global_load_dwordx4 v[132:135], v172, s[24:25]
	s_sub_i32 s21, s20, 7
	s_max_i32 s21, s21, 0
	s_mul_i32 s21, s21, 0x1200
	s_add_u32 s24, s90, s21
	s_addc_u32 s25, s91, 0
	global_load_dwordx4 v[136:139], v172, s[24:25]
	s_sub_i32 s21, s20, 8
	s_max_i32 s21, s21, 0
	s_mul_i32 s21, s21, 0x1200
	s_add_u32 s24, s90, s21
	s_addc_u32 s25, s91, 0
	global_load_dwordx4 v[140:143], v172, s[24:25]
	s_sub_i32 s21, s20, 9
	s_max_i32 s21, s21, 0
	s_mul_i32 s21, s21, 0x1200
	s_add_u32 s24, s90, s21
	s_addc_u32 s25, s91, 0
	global_load_dwordx4 v[144:147], v172, s[24:25]
	s_sub_i32 s21, s20, 10
	s_max_i32 s21, s21, 0
	s_mul_i32 s21, s21, 0x1200
	s_add_u32 s24, s90, s21
	s_addc_u32 s25, s91, 0
	global_load_dwordx4 v[148:151], v172, s[24:25]
	s_sub_i32 s21, s20, 11
	s_max_i32 s21, s21, 0
	s_mul_i32 s21, s21, 0x1200
	s_add_u32 s24, s90, s21
	s_addc_u32 s25, s91, 0
	global_load_dwordx4 v[152:155], v172, s[24:25]
	s_sub_i32 s21, s20, 12
	s_max_i32 s21, s21, 0
	s_mul_i32 s21, s21, 0x1200
	s_add_u32 s24, s90, s21
	s_addc_u32 s25, s91, 0
	global_load_dwordx4 v[156:159], v172, s[24:25]
	s_sub_i32 s21, s20, 13
	s_max_i32 s21, s21, 0
	s_mul_i32 s21, s21, 0x1200
	s_add_u32 s24, s90, s21
	s_addc_u32 s25, s91, 0
	global_load_dwordx4 v[160:163], v172, s[24:25]
	s_sub_i32 s21, s20, 14
	s_max_i32 s21, s21, 0
	s_mul_i32 s21, s21, 0x1200
	s_add_u32 s24, s90, s21
	s_addc_u32 s25, s91, 0
	global_load_dwordx4 v[164:167], v172, s[24:25]
	s_sub_i32 s21, s20, 15
	s_max_i32 s21, s21, 0
	s_mul_i32 s21, s21, 0x1200
	s_add_u32 s24, s90, s21
	s_addc_u32 s25, s91, 0
	global_load_dwordx4 v[168:171], v172, s[24:25]
	s_waitcnt vmcnt(17)
	v_lshlrev_b32_e32 v182, 16, v44
	v_and_b32_e32 v183, 0xffff0000, v44
	v_lshlrev_b32_e32 v180, 16, v45
	v_and_b32_e32 v181, 0xffff0000, v45
	v_lshlrev_b32_e32 v178, 16, v46
	v_and_b32_e32 v179, 0xffff0000, v46
	v_lshlrev_b32_e32 v176, 16, v47
	v_and_b32_e32 v177, 0xffff0000, v47
	v_mov_b32_e32 v184, v176
	v_mov_b32_e32 v185, v177
	v_mov_b32_e32 v186, v178
	v_mov_b32_e32 v187, v179
	v_mov_b32_e32 v188, v180
	v_mov_b32_e32 v189, v181
	v_mov_b32_e32 v190, v182
	v_mov_b32_e32 v191, v183
	s_mov_b64 s[26:27], exec
	v_cmp_lt_u32_e32 vcc, 1, v173
	s_and_b64 exec, exec, vcc
	v_lshlrev_b32_e32 v198, 16, v48
	v_and_b32_e32 v199, 0xffff0000, v48
	v_lshlrev_b32_e32 v196, 16, v49
	v_and_b32_e32 v197, 0xffff0000, v49
	v_lshlrev_b32_e32 v194, 16, v50
	v_and_b32_e32 v195, 0xffff0000, v50
	v_lshlrev_b32_e32 v192, 16, v51
	v_and_b32_e32 v193, 0xffff0000, v51
	v_pk_add_f32 v[184:185], v[184:185], v[192:193]
	v_pk_add_f32 v[186:187], v[186:187], v[194:195]
	v_pk_add_f32 v[188:189], v[188:189], v[196:197]
	v_pk_add_f32 v[190:191], v[190:191], v[198:199]
	v_cmp_lt_u32_e32 vcc, 2, v173
	s_and_b64 exec, exec, vcc
	v_lshlrev_b32_e32 v198, 16, v52
	v_and_b32_e32 v199, 0xffff0000, v52
	v_lshlrev_b32_e32 v196, 16, v53
	v_and_b32_e32 v197, 0xffff0000, v53
	v_lshlrev_b32_e32 v194, 16, v54
	v_and_b32_e32 v195, 0xffff0000, v54
	v_lshlrev_b32_e32 v192, 16, v55
	v_and_b32_e32 v193, 0xffff0000, v55
	v_pk_add_f32 v[184:185], v[184:185], v[192:193]
	v_pk_add_f32 v[186:187], v[186:187], v[194:195]
	v_pk_add_f32 v[188:189], v[188:189], v[196:197]
	v_pk_add_f32 v[190:191], v[190:191], v[198:199]
	v_cmp_lt_u32_e32 vcc, 3, v173
	s_and_b64 exec, exec, vcc
	v_lshlrev_b32_e32 v198, 16, v56
	v_and_b32_e32 v199, 0xffff0000, v56
	v_lshlrev_b32_e32 v196, 16, v57
	v_and_b32_e32 v197, 0xffff0000, v57
	v_lshlrev_b32_e32 v194, 16, v58
	v_and_b32_e32 v195, 0xffff0000, v58
	v_lshlrev_b32_e32 v192, 16, v59
	v_and_b32_e32 v193, 0xffff0000, v59
	v_pk_add_f32 v[184:185], v[184:185], v[192:193]
	v_pk_add_f32 v[186:187], v[186:187], v[194:195]
	v_pk_add_f32 v[188:189], v[188:189], v[196:197]
	v_pk_add_f32 v[190:191], v[190:191], v[198:199]
	v_cmp_lt_u32_e32 vcc, 4, v173
	s_and_b64 exec, exec, vcc
	v_lshlrev_b32_e32 v198, 16, v60
	v_and_b32_e32 v199, 0xffff0000, v60
	v_lshlrev_b32_e32 v196, 16, v61
	v_and_b32_e32 v197, 0xffff0000, v61
	v_lshlrev_b32_e32 v194, 16, v62
	v_and_b32_e32 v195, 0xffff0000, v62
	v_lshlrev_b32_e32 v192, 16, v63
	v_and_b32_e32 v193, 0xffff0000, v63
	v_pk_add_f32 v[184:185], v[184:185], v[192:193]
	v_pk_add_f32 v[186:187], v[186:187], v[194:195]
	v_pk_add_f32 v[188:189], v[188:189], v[196:197]
	v_pk_add_f32 v[190:191], v[190:191], v[198:199]
	v_cmp_lt_u32_e32 vcc, 5, v173
	s_and_b64 exec, exec, vcc
	v_lshlrev_b32_e32 v198, 16, v64
	v_and_b32_e32 v199, 0xffff0000, v64
	v_lshlrev_b32_e32 v196, 16, v65
	v_and_b32_e32 v197, 0xffff0000, v65
	v_lshlrev_b32_e32 v194, 16, v66
	v_and_b32_e32 v195, 0xffff0000, v66
	v_lshlrev_b32_e32 v192, 16, v67
	v_and_b32_e32 v193, 0xffff0000, v67
	v_pk_add_f32 v[184:185], v[184:185], v[192:193]
	v_pk_add_f32 v[186:187], v[186:187], v[194:195]
	v_pk_add_f32 v[188:189], v[188:189], v[196:197]
	v_pk_add_f32 v[190:191], v[190:191], v[198:199]
	v_cmp_lt_u32_e32 vcc, 6, v173
	s_and_b64 exec, exec, vcc
	v_lshlrev_b32_e32 v198, 16, v68
	v_and_b32_e32 v199, 0xffff0000, v68
	v_lshlrev_b32_e32 v196, 16, v69
	v_and_b32_e32 v197, 0xffff0000, v69
	v_lshlrev_b32_e32 v194, 16, v70
	v_and_b32_e32 v195, 0xffff0000, v70
	v_lshlrev_b32_e32 v192, 16, v71
	v_and_b32_e32 v193, 0xffff0000, v71
	v_pk_add_f32 v[184:185], v[184:185], v[192:193]
	v_pk_add_f32 v[186:187], v[186:187], v[194:195]
	v_pk_add_f32 v[188:189], v[188:189], v[196:197]
	v_pk_add_f32 v[190:191], v[190:191], v[198:199]
	v_cmp_lt_u32_e32 vcc, 7, v173
	s_and_b64 exec, exec, vcc
	v_lshlrev_b32_e32 v198, 16, v72
	v_and_b32_e32 v199, 0xffff0000, v72
	v_lshlrev_b32_e32 v196, 16, v73
	v_and_b32_e32 v197, 0xffff0000, v73
	v_lshlrev_b32_e32 v194, 16, v74
	v_and_b32_e32 v195, 0xffff0000, v74
	v_lshlrev_b32_e32 v192, 16, v75
	v_and_b32_e32 v193, 0xffff0000, v75
	v_pk_add_f32 v[184:185], v[184:185], v[192:193]
	v_pk_add_f32 v[186:187], v[186:187], v[194:195]
	v_pk_add_f32 v[188:189], v[188:189], v[196:197]
	v_pk_add_f32 v[190:191], v[190:191], v[198:199]
	v_cmp_lt_u32_e32 vcc, 8, v173
	s_and_b64 exec, exec, vcc
	v_lshlrev_b32_e32 v198, 16, v76
	v_and_b32_e32 v199, 0xffff0000, v76
	v_lshlrev_b32_e32 v196, 16, v77
	v_and_b32_e32 v197, 0xffff0000, v77
	v_lshlrev_b32_e32 v194, 16, v78
	v_and_b32_e32 v195, 0xffff0000, v78
	v_lshlrev_b32_e32 v192, 16, v79
	v_and_b32_e32 v193, 0xffff0000, v79
	v_pk_add_f32 v[184:185], v[184:185], v[192:193]
	v_pk_add_f32 v[186:187], v[186:187], v[194:195]
	v_pk_add_f32 v[188:189], v[188:189], v[196:197]
	v_pk_add_f32 v[190:191], v[190:191], v[198:199]
	v_cmp_lt_u32_e32 vcc, 9, v173
	s_and_b64 exec, exec, vcc
	v_lshlrev_b32_e32 v198, 16, v80
	v_and_b32_e32 v199, 0xffff0000, v80
	v_lshlrev_b32_e32 v196, 16, v81
	v_and_b32_e32 v197, 0xffff0000, v81
	v_lshlrev_b32_e32 v194, 16, v82
	v_and_b32_e32 v195, 0xffff0000, v82
	v_lshlrev_b32_e32 v192, 16, v83
	v_and_b32_e32 v193, 0xffff0000, v83
	v_pk_add_f32 v[184:185], v[184:185], v[192:193]
	v_pk_add_f32 v[186:187], v[186:187], v[194:195]
	v_pk_add_f32 v[188:189], v[188:189], v[196:197]
	v_pk_add_f32 v[190:191], v[190:191], v[198:199]
	v_cmp_lt_u32_e32 vcc, 10, v173
	s_and_b64 exec, exec, vcc
	v_lshlrev_b32_e32 v198, 16, v84
	v_and_b32_e32 v199, 0xffff0000, v84
	v_lshlrev_b32_e32 v196, 16, v85
	v_and_b32_e32 v197, 0xffff0000, v85
	v_lshlrev_b32_e32 v194, 16, v86
	v_and_b32_e32 v195, 0xffff0000, v86
	v_lshlrev_b32_e32 v192, 16, v87
	v_and_b32_e32 v193, 0xffff0000, v87
	v_pk_add_f32 v[184:185], v[184:185], v[192:193]
	v_pk_add_f32 v[186:187], v[186:187], v[194:195]
	v_pk_add_f32 v[188:189], v[188:189], v[196:197]
	v_pk_add_f32 v[190:191], v[190:191], v[198:199]
	v_cmp_lt_u32_e32 vcc, 11, v173
	s_and_b64 exec, exec, vcc
	v_lshlrev_b32_e32 v198, 16, v88
	v_and_b32_e32 v199, 0xffff0000, v88
	v_lshlrev_b32_e32 v196, 16, v89
	v_and_b32_e32 v197, 0xffff0000, v89
	v_lshlrev_b32_e32 v194, 16, v90
	v_and_b32_e32 v195, 0xffff0000, v90
	v_lshlrev_b32_e32 v192, 16, v91
	v_and_b32_e32 v193, 0xffff0000, v91
	v_pk_add_f32 v[184:185], v[184:185], v[192:193]
	v_pk_add_f32 v[186:187], v[186:187], v[194:195]
	v_pk_add_f32 v[188:189], v[188:189], v[196:197]
	v_pk_add_f32 v[190:191], v[190:191], v[198:199]
	v_cmp_lt_u32_e32 vcc, 12, v173
	s_and_b64 exec, exec, vcc
	v_lshlrev_b32_e32 v198, 16, v92
	v_and_b32_e32 v199, 0xffff0000, v92
	v_lshlrev_b32_e32 v196, 16, v93
	v_and_b32_e32 v197, 0xffff0000, v93
	v_lshlrev_b32_e32 v194, 16, v94
	v_and_b32_e32 v195, 0xffff0000, v94
	v_lshlrev_b32_e32 v192, 16, v95
	v_and_b32_e32 v193, 0xffff0000, v95
	v_pk_add_f32 v[184:185], v[184:185], v[192:193]
	v_pk_add_f32 v[186:187], v[186:187], v[194:195]
	v_pk_add_f32 v[188:189], v[188:189], v[196:197]
	v_pk_add_f32 v[190:191], v[190:191], v[198:199]
	v_cmp_lt_u32_e32 vcc, 13, v173
	s_and_b64 exec, exec, vcc
	v_lshlrev_b32_e32 v198, 16, v96
	v_and_b32_e32 v199, 0xffff0000, v96
	v_lshlrev_b32_e32 v196, 16, v97
	v_and_b32_e32 v197, 0xffff0000, v97
	v_lshlrev_b32_e32 v194, 16, v98
	v_and_b32_e32 v195, 0xffff0000, v98
	v_lshlrev_b32_e32 v192, 16, v99
	v_and_b32_e32 v193, 0xffff0000, v99
	v_pk_add_f32 v[184:185], v[184:185], v[192:193]
	v_pk_add_f32 v[186:187], v[186:187], v[194:195]
	v_pk_add_f32 v[188:189], v[188:189], v[196:197]
	v_pk_add_f32 v[190:191], v[190:191], v[198:199]
	v_cmp_lt_u32_e32 vcc, 14, v173
	s_and_b64 exec, exec, vcc
	v_lshlrev_b32_e32 v198, 16, v100
	v_and_b32_e32 v199, 0xffff0000, v100
	v_lshlrev_b32_e32 v196, 16, v101
	v_and_b32_e32 v197, 0xffff0000, v101
	v_lshlrev_b32_e32 v194, 16, v102
	v_and_b32_e32 v195, 0xffff0000, v102
	v_lshlrev_b32_e32 v192, 16, v103
	v_and_b32_e32 v193, 0xffff0000, v103
	v_pk_add_f32 v[184:185], v[184:185], v[192:193]
	v_pk_add_f32 v[186:187], v[186:187], v[194:195]
	v_pk_add_f32 v[188:189], v[188:189], v[196:197]
	v_pk_add_f32 v[190:191], v[190:191], v[198:199]
	v_cmp_lt_u32_e32 vcc, 15, v173
	s_and_b64 exec, exec, vcc
	v_lshlrev_b32_e32 v198, 16, v104
	v_and_b32_e32 v199, 0xffff0000, v104
	v_lshlrev_b32_e32 v196, 16, v105
	v_and_b32_e32 v197, 0xffff0000, v105
	v_lshlrev_b32_e32 v194, 16, v106
	v_and_b32_e32 v195, 0xffff0000, v106
	v_lshlrev_b32_e32 v192, 16, v107
	v_and_b32_e32 v193, 0xffff0000, v107
	v_pk_add_f32 v[184:185], v[184:185], v[192:193]
	v_pk_add_f32 v[186:187], v[186:187], v[194:195]
	v_pk_add_f32 v[188:189], v[188:189], v[196:197]
	v_pk_add_f32 v[190:191], v[190:191], v[198:199]
	s_mov_b64 exec, s[26:27]
	v_pk_fma_f32 v[184:185], v[184:185], v[174:175], v[176:177] op_sel_hi:[1,0,1] neg_lo:[0,0,1] neg_hi:[0,0,1]
	v_pk_fma_f32 v[186:187], v[186:187], v[174:175], v[178:179] op_sel_hi:[1,0,1] neg_lo:[0,0,1] neg_hi:[0,0,1]
	v_pk_fma_f32 v[188:189], v[188:189], v[174:175], v[180:181] op_sel_hi:[1,0,1] neg_lo:[0,0,1] neg_hi:[0,0,1]
	v_pk_fma_f32 v[190:191], v[190:191], v[174:175], v[182:183] op_sel_hi:[1,0,1] neg_lo:[0,0,1] neg_hi:[0,0,1]
	v_cvt_pk_bf16_f32 v200, v190, v191
	v_cvt_pk_bf16_f32 v201, v188, v189
	v_cvt_pk_bf16_f32 v202, v186, v187
	v_cvt_pk_bf16_f32 v203, v184, v185
	s_lshl_b32 s21, s22, 10
	s_add_u32 s24, s88, s21
	s_addc_u32 s25, s89, 0
	global_store_dwordx4 v175, v[200:203], s[24:25]
	s_add_i32 s22, s22, 0x800
	s_waitcnt vmcnt(1)
	v_lshlrev_b32_e32 v182, 16, v108
	v_and_b32_e32 v183, 0xffff0000, v108
	v_lshlrev_b32_e32 v180, 16, v109
	v_and_b32_e32 v181, 0xffff0000, v109
	v_lshlrev_b32_e32 v178, 16, v110
	v_and_b32_e32 v179, 0xffff0000, v110
	v_lshlrev_b32_e32 v176, 16, v111
	v_and_b32_e32 v177, 0xffff0000, v111
	v_mov_b32_e32 v184, v176
	v_mov_b32_e32 v185, v177
	v_mov_b32_e32 v186, v178
	v_mov_b32_e32 v187, v179
	v_mov_b32_e32 v188, v180
	v_mov_b32_e32 v189, v181
	v_mov_b32_e32 v190, v182
	v_mov_b32_e32 v191, v183
	s_mov_b64 s[26:27], exec
	v_cmp_lt_u32_e32 vcc, 1, v173
	s_and_b64 exec, exec, vcc
	v_lshlrev_b32_e32 v198, 16, v112
	v_and_b32_e32 v199, 0xffff0000, v112
	v_lshlrev_b32_e32 v196, 16, v113
	v_and_b32_e32 v197, 0xffff0000, v113
	v_lshlrev_b32_e32 v194, 16, v114
	v_and_b32_e32 v195, 0xffff0000, v114
	v_lshlrev_b32_e32 v192, 16, v115
	v_and_b32_e32 v193, 0xffff0000, v115
	v_pk_add_f32 v[184:185], v[184:185], v[192:193]
	v_pk_add_f32 v[186:187], v[186:187], v[194:195]
	v_pk_add_f32 v[188:189], v[188:189], v[196:197]
	v_pk_add_f32 v[190:191], v[190:191], v[198:199]
	v_cmp_lt_u32_e32 vcc, 2, v173
	s_and_b64 exec, exec, vcc
	v_lshlrev_b32_e32 v198, 16, v116
	v_and_b32_e32 v199, 0xffff0000, v116
	v_lshlrev_b32_e32 v196, 16, v117
	v_and_b32_e32 v197, 0xffff0000, v117
	v_lshlrev_b32_e32 v194, 16, v118
	v_and_b32_e32 v195, 0xffff0000, v118
	v_lshlrev_b32_e32 v192, 16, v119
	v_and_b32_e32 v193, 0xffff0000, v119
	v_pk_add_f32 v[184:185], v[184:185], v[192:193]
	v_pk_add_f32 v[186:187], v[186:187], v[194:195]
	v_pk_add_f32 v[188:189], v[188:189], v[196:197]
	v_pk_add_f32 v[190:191], v[190:191], v[198:199]
	v_cmp_lt_u32_e32 vcc, 3, v173
	s_and_b64 exec, exec, vcc
	v_lshlrev_b32_e32 v198, 16, v120
	v_and_b32_e32 v199, 0xffff0000, v120
	v_lshlrev_b32_e32 v196, 16, v121
	v_and_b32_e32 v197, 0xffff0000, v121
	v_lshlrev_b32_e32 v194, 16, v122
	v_and_b32_e32 v195, 0xffff0000, v122
	v_lshlrev_b32_e32 v192, 16, v123
	v_and_b32_e32 v193, 0xffff0000, v123
	v_pk_add_f32 v[184:185], v[184:185], v[192:193]
	v_pk_add_f32 v[186:187], v[186:187], v[194:195]
	v_pk_add_f32 v[188:189], v[188:189], v[196:197]
	v_pk_add_f32 v[190:191], v[190:191], v[198:199]
	v_cmp_lt_u32_e32 vcc, 4, v173
	s_and_b64 exec, exec, vcc
	v_lshlrev_b32_e32 v198, 16, v124
	v_and_b32_e32 v199, 0xffff0000, v124
	v_lshlrev_b32_e32 v196, 16, v125
	v_and_b32_e32 v197, 0xffff0000, v125
	v_lshlrev_b32_e32 v194, 16, v126
	v_and_b32_e32 v195, 0xffff0000, v126
	v_lshlrev_b32_e32 v192, 16, v127
	v_and_b32_e32 v193, 0xffff0000, v127
	v_pk_add_f32 v[184:185], v[184:185], v[192:193]
	v_pk_add_f32 v[186:187], v[186:187], v[194:195]
	v_pk_add_f32 v[188:189], v[188:189], v[196:197]
	v_pk_add_f32 v[190:191], v[190:191], v[198:199]
	v_cmp_lt_u32_e32 vcc, 5, v173
	s_and_b64 exec, exec, vcc
	v_lshlrev_b32_e32 v198, 16, v128
	v_and_b32_e32 v199, 0xffff0000, v128
	v_lshlrev_b32_e32 v196, 16, v129
	v_and_b32_e32 v197, 0xffff0000, v129
	v_lshlrev_b32_e32 v194, 16, v130
	v_and_b32_e32 v195, 0xffff0000, v130
	v_lshlrev_b32_e32 v192, 16, v131
	v_and_b32_e32 v193, 0xffff0000, v131
	v_pk_add_f32 v[184:185], v[184:185], v[192:193]
	v_pk_add_f32 v[186:187], v[186:187], v[194:195]
	v_pk_add_f32 v[188:189], v[188:189], v[196:197]
	v_pk_add_f32 v[190:191], v[190:191], v[198:199]
	v_cmp_lt_u32_e32 vcc, 6, v173
	s_and_b64 exec, exec, vcc
	v_lshlrev_b32_e32 v198, 16, v132
	v_and_b32_e32 v199, 0xffff0000, v132
	v_lshlrev_b32_e32 v196, 16, v133
	v_and_b32_e32 v197, 0xffff0000, v133
	v_lshlrev_b32_e32 v194, 16, v134
	v_and_b32_e32 v195, 0xffff0000, v134
	v_lshlrev_b32_e32 v192, 16, v135
	v_and_b32_e32 v193, 0xffff0000, v135
	v_pk_add_f32 v[184:185], v[184:185], v[192:193]
	v_pk_add_f32 v[186:187], v[186:187], v[194:195]
	v_pk_add_f32 v[188:189], v[188:189], v[196:197]
	v_pk_add_f32 v[190:191], v[190:191], v[198:199]
	v_cmp_lt_u32_e32 vcc, 7, v173
	s_and_b64 exec, exec, vcc
	v_lshlrev_b32_e32 v198, 16, v136
	v_and_b32_e32 v199, 0xffff0000, v136
	v_lshlrev_b32_e32 v196, 16, v137
	v_and_b32_e32 v197, 0xffff0000, v137
	v_lshlrev_b32_e32 v194, 16, v138
	v_and_b32_e32 v195, 0xffff0000, v138
	v_lshlrev_b32_e32 v192, 16, v139
	v_and_b32_e32 v193, 0xffff0000, v139
	v_pk_add_f32 v[184:185], v[184:185], v[192:193]
	v_pk_add_f32 v[186:187], v[186:187], v[194:195]
	v_pk_add_f32 v[188:189], v[188:189], v[196:197]
	v_pk_add_f32 v[190:191], v[190:191], v[198:199]
	v_cmp_lt_u32_e32 vcc, 8, v173
	s_and_b64 exec, exec, vcc
	v_lshlrev_b32_e32 v198, 16, v140
	v_and_b32_e32 v199, 0xffff0000, v140
	v_lshlrev_b32_e32 v196, 16, v141
	v_and_b32_e32 v197, 0xffff0000, v141
	v_lshlrev_b32_e32 v194, 16, v142
	v_and_b32_e32 v195, 0xffff0000, v142
	v_lshlrev_b32_e32 v192, 16, v143
	v_and_b32_e32 v193, 0xffff0000, v143
	v_pk_add_f32 v[184:185], v[184:185], v[192:193]
	v_pk_add_f32 v[186:187], v[186:187], v[194:195]
	v_pk_add_f32 v[188:189], v[188:189], v[196:197]
	v_pk_add_f32 v[190:191], v[190:191], v[198:199]
	v_cmp_lt_u32_e32 vcc, 9, v173
	s_and_b64 exec, exec, vcc
	v_lshlrev_b32_e32 v198, 16, v144
	v_and_b32_e32 v199, 0xffff0000, v144
	v_lshlrev_b32_e32 v196, 16, v145
	v_and_b32_e32 v197, 0xffff0000, v145
	v_lshlrev_b32_e32 v194, 16, v146
	v_and_b32_e32 v195, 0xffff0000, v146
	v_lshlrev_b32_e32 v192, 16, v147
	v_and_b32_e32 v193, 0xffff0000, v147
	v_pk_add_f32 v[184:185], v[184:185], v[192:193]
	v_pk_add_f32 v[186:187], v[186:187], v[194:195]
	v_pk_add_f32 v[188:189], v[188:189], v[196:197]
	v_pk_add_f32 v[190:191], v[190:191], v[198:199]
	v_cmp_lt_u32_e32 vcc, 10, v173
	s_and_b64 exec, exec, vcc
	v_lshlrev_b32_e32 v198, 16, v148
	v_and_b32_e32 v199, 0xffff0000, v148
	v_lshlrev_b32_e32 v196, 16, v149
	v_and_b32_e32 v197, 0xffff0000, v149
	v_lshlrev_b32_e32 v194, 16, v150
	v_and_b32_e32 v195, 0xffff0000, v150
	v_lshlrev_b32_e32 v192, 16, v151
	v_and_b32_e32 v193, 0xffff0000, v151
	v_pk_add_f32 v[184:185], v[184:185], v[192:193]
	v_pk_add_f32 v[186:187], v[186:187], v[194:195]
	v_pk_add_f32 v[188:189], v[188:189], v[196:197]
	v_pk_add_f32 v[190:191], v[190:191], v[198:199]
	v_cmp_lt_u32_e32 vcc, 11, v173
	s_and_b64 exec, exec, vcc
	v_lshlrev_b32_e32 v198, 16, v152
	v_and_b32_e32 v199, 0xffff0000, v152
	v_lshlrev_b32_e32 v196, 16, v153
	v_and_b32_e32 v197, 0xffff0000, v153
	v_lshlrev_b32_e32 v194, 16, v154
	v_and_b32_e32 v195, 0xffff0000, v154
	v_lshlrev_b32_e32 v192, 16, v155
	v_and_b32_e32 v193, 0xffff0000, v155
	v_pk_add_f32 v[184:185], v[184:185], v[192:193]
	v_pk_add_f32 v[186:187], v[186:187], v[194:195]
	v_pk_add_f32 v[188:189], v[188:189], v[196:197]
	v_pk_add_f32 v[190:191], v[190:191], v[198:199]
	v_cmp_lt_u32_e32 vcc, 12, v173
	s_and_b64 exec, exec, vcc
	v_lshlrev_b32_e32 v198, 16, v156
	v_and_b32_e32 v199, 0xffff0000, v156
	v_lshlrev_b32_e32 v196, 16, v157
	v_and_b32_e32 v197, 0xffff0000, v157
	v_lshlrev_b32_e32 v194, 16, v158
	v_and_b32_e32 v195, 0xffff0000, v158
	v_lshlrev_b32_e32 v192, 16, v159
	v_and_b32_e32 v193, 0xffff0000, v159
	v_pk_add_f32 v[184:185], v[184:185], v[192:193]
	v_pk_add_f32 v[186:187], v[186:187], v[194:195]
	v_pk_add_f32 v[188:189], v[188:189], v[196:197]
	v_pk_add_f32 v[190:191], v[190:191], v[198:199]
	v_cmp_lt_u32_e32 vcc, 13, v173
	s_and_b64 exec, exec, vcc
	v_lshlrev_b32_e32 v198, 16, v160
	v_and_b32_e32 v199, 0xffff0000, v160
	v_lshlrev_b32_e32 v196, 16, v161
	v_and_b32_e32 v197, 0xffff0000, v161
	v_lshlrev_b32_e32 v194, 16, v162
	v_and_b32_e32 v195, 0xffff0000, v162
	v_lshlrev_b32_e32 v192, 16, v163
	v_and_b32_e32 v193, 0xffff0000, v163
	v_pk_add_f32 v[184:185], v[184:185], v[192:193]
	v_pk_add_f32 v[186:187], v[186:187], v[194:195]
	v_pk_add_f32 v[188:189], v[188:189], v[196:197]
	v_pk_add_f32 v[190:191], v[190:191], v[198:199]
	v_cmp_lt_u32_e32 vcc, 14, v173
	s_and_b64 exec, exec, vcc
	v_lshlrev_b32_e32 v198, 16, v164
	v_and_b32_e32 v199, 0xffff0000, v164
	v_lshlrev_b32_e32 v196, 16, v165
	v_and_b32_e32 v197, 0xffff0000, v165
	v_lshlrev_b32_e32 v194, 16, v166
	v_and_b32_e32 v195, 0xffff0000, v166
	v_lshlrev_b32_e32 v192, 16, v167
	v_and_b32_e32 v193, 0xffff0000, v167
	v_pk_add_f32 v[184:185], v[184:185], v[192:193]
	v_pk_add_f32 v[186:187], v[186:187], v[194:195]
	v_pk_add_f32 v[188:189], v[188:189], v[196:197]
	v_pk_add_f32 v[190:191], v[190:191], v[198:199]
	v_cmp_lt_u32_e32 vcc, 15, v173
	s_and_b64 exec, exec, vcc
	v_lshlrev_b32_e32 v198, 16, v168
	v_and_b32_e32 v199, 0xffff0000, v168
	v_lshlrev_b32_e32 v196, 16, v169
	v_and_b32_e32 v197, 0xffff0000, v169
	v_lshlrev_b32_e32 v194, 16, v170
	v_and_b32_e32 v195, 0xffff0000, v170
	v_lshlrev_b32_e32 v192, 16, v171
	v_and_b32_e32 v193, 0xffff0000, v171
	v_pk_add_f32 v[184:185], v[184:185], v[192:193]
	v_pk_add_f32 v[186:187], v[186:187], v[194:195]
	v_pk_add_f32 v[188:189], v[188:189], v[196:197]
	v_pk_add_f32 v[190:191], v[190:191], v[198:199]
	s_mov_b64 exec, s[26:27]
	v_pk_fma_f32 v[184:185], v[184:185], v[174:175], v[176:177] op_sel_hi:[1,0,1] neg_lo:[0,0,1] neg_hi:[0,0,1]
	v_pk_fma_f32 v[186:187], v[186:187], v[174:175], v[178:179] op_sel_hi:[1,0,1] neg_lo:[0,0,1] neg_hi:[0,0,1]
	v_pk_fma_f32 v[188:189], v[188:189], v[174:175], v[180:181] op_sel_hi:[1,0,1] neg_lo:[0,0,1] neg_hi:[0,0,1]
	v_pk_fma_f32 v[190:191], v[190:191], v[174:175], v[182:183] op_sel_hi:[1,0,1] neg_lo:[0,0,1] neg_hi:[0,0,1]
	v_cvt_pk_bf16_f32 v200, v190, v191
	v_cvt_pk_bf16_f32 v201, v188, v189
	v_cvt_pk_bf16_f32 v202, v186, v187
	v_cvt_pk_bf16_f32 v203, v184, v185
	s_lshl_b32 s21, s22, 10
	s_add_u32 s24, s88, s21
	s_addc_u32 s25, s89, 0
	global_store_dwordx4 v175, v[200:203], s[24:25]
	s_add_i32 s22, s22, 0x800
	s_add_i32 s8, s2, 0x1000
	s_cmpk_gt_i32 s8, 0x107f
	s_cbranch_scc1 .LBB0_271
	s_branch .LBB0_258
.Lpool_skip:
	s_branch .LBB0_258
.LBB0_256:
	s_or_b64 exec, exec, s[4:5]
